# A1 and D: a workgroup handles units u and u+2, its neighbour u+1 and u+3, so neighbours work on adjacent query blocks at the same time
# baseline (speedup 1.0000x reference)
; #define LAS __attribute__((address_space(3)))
; DI float ex2(float x) { return __builtin_amdgcn_exp2f(x); }
; DI float a_bound(const bf16x8 (&qf)[2], const float* kmax_l, int b, int h) { return sqrtf(q_norm2(qf) * (kmax_l[b * 128 + 8 + 2 * h] + kmax_l[b * 128 + 9 + 2 * h])) * 1.01f + 0.05f; }
; #define LAUNDER() int tp = TID0(); const int tid = tp, lane = tp & 63, wave = __builtin_amdgcn_readfirstlane(tp >> 6); (void)tid; (void)lane; (void)wave
; DI void mixerA1_unit(int u, const bf16* PROJ, bf16* YC, float* LPA, const float* kmax_l, LAS char* vt, int wave, int lane) {
;     const int b = u >> 6, h = (u >> 4) & 3, qblk = u & 15, r = lane & 15, g = lane >> 4;
;     const bf16* kb = slab(PROJ, C_AK + h * 64, b); const bf16* vb = slab(PROJ, C_AV + h * 64, b);
;     const int t0 = qblk * 128 + wave * 16, tq = t0 + r;
;     bf16x8 qf[2];
; #pragma unroll
;     for (int ks = 0; ks < 2; ++ks) qf[ks] = *(const bf16x8*)(slab(PROJ, C_AQ + h * 64, b) + (size_t)tq * 64 + 32 * ks + 8 * g);
;     const float nslope2 = -ex2(-(float)(2 * h + 1)) * LOG2E;
;     const float bound = a_bound(qf, kmax_l, b, h);
;     const f32x4 cinit = {-bound, -bound, -bound, -bound};
;     f32x4 o[4], ol = {0.f, 0.f, 0.f, 0.f};
; #pragma unroll
;     for (int c = 0; c < 4; ++c) o[c] = ol;
;     TileRegs R0, R1, R2;
;     const int tb0 = t0 - 64;
;     tile_load(R0, kb, vb, tb0, 1, lane); tile_load(R1, kb, vb, tb0 + 32, 1, lane); tile_load(R2, kb, vb, tb0 + 64, 1, lane);
;     f32x4 sA[2], sB[2];
; __global__ void __launch_bounds__(512) fwd_kernel(Args a) {
;     ...
;             if (EN_A) { LAUNDER(); LAS char* vt = (LAS char*)lds + wave * 16384;
;                 for (int u = blockIdx.x; u < 512; u += G) { mixerA1_unit(u, PROJ, YC, LPA, KMAX + l * 1024, vt, wave, lane); } }
.LBB0_356:
	v_readlane_b32 s0, v253, 0
	v_readlane_b32 s4, v254, 31
	s_waitcnt vmcnt(63) expcnt(7) lgkmcnt(15)
	s_barrier
	v_mbcnt_lo_u32_b32 v4, -1, 0
	v_mbcnt_hi_u32_b32 v4, -1, v4
	v_readlane_b32 s5, v254, 32
	v_add_u32_e32 v5, s0, v4
	v_readlane_b32 s94, v255, 33
	v_readfirstlane_b32 s0, v5
	v_cndmask_b32_e64 v5, 0, 1, s[4:5]
	v_readlane_b32 s96, v255, 19
	v_cmp_ne_u32_e64 s[36:37], 1, v5
	s_andn2_b64 vcc, exec, s[4:5]
	v_readlane_b32 s95, v255, 34
	v_readlane_b32 s97, v255, 20
	s_cbranch_vccnz .LBB0_361
	s_ashr_i32 s5, s0, 6
	s_lshl_b32 s0, s5, 14
	s_add_i32 s16, s0, 0
	v_readlane_b32 s0, v255, 27
	v_readlane_b32 s1, v255, 28
	s_lshl_b32 s34, s0, 10
	s_lshl_b64 s[0:1], s[34:35], 2
	v_readlane_b32 s20, v253, 42
	v_bfe_u32 v7, v4, 4, 2
	s_add_u32 s2, s20, s0
	v_and_b32_e32 v109, 15, v4
	v_lshlrev_b32_e32 v131, 2, v7
	v_mov_b32_e32 v10, s16
	s_movk_i32 s0, 0x90
	v_bfe_u32 v11, v4, 2, 4
	v_mad_u32_u24 v132, v109, s0, v10
	v_mad_u32_u24 v10, v11, s0, v10
	v_sub_u32_e32 v11, v131, v109
	v_add_u32_e32 v12, 1, v11
	v_and_b32_e32 v8, 64, v224
	v_cvt_f32_i32_e32 v134, v12
	v_add_u32_e32 v12, 2, v11
	v_xor_b32_e32 v6, 16, v224
	v_add_u32_e32 v8, 64, v8
	v_cvt_f32_i32_e32 v135, v12
	v_add_u32_e32 v12, 3, v11
	v_cmp_lt_i32_e32 vcc, v6, v8
	v_cvt_f32_i32_e32 v136, v12
	v_add_u32_e32 v12, 16, v11
	v_cndmask_b32_e32 v6, v224, v6, vcc
	v_cvt_f32_u32_e32 v137, v12
	v_add_u32_e32 v12, 17, v11
	v_lshlrev_b32_e32 v124, 2, v6
	v_xor_b32_e32 v6, 32, v224
	v_cvt_f32_i32_e32 v133, v11
	v_cvt_f32_u32_e32 v138, v12
	v_add_u32_e32 v12, 18, v11
	v_add_u32_e32 v11, 19, v11
	v_and_b32_e32 v5, 63, v4
	v_cmp_lt_i32_e32 vcc, v6, v8
	v_bfe_u32 v126, v4, 3, 3
	v_lshlrev_b32_e32 v9, 4, v4
	v_cvt_f32_u32_e32 v139, v12
	v_cvt_f32_u32_e32 v140, v11
	v_lshlrev_b32_e32 v108, 3, v7
	v_cndmask_b32_e32 v6, v224, v6, vcc
	v_lshlrev_b32_e32 v8, 3, v5
	v_or_b32_e32 v127, 8, v126
	v_and_b32_e32 v9, 0x70, v9
	v_and_b32_e32 v7, 48, v4
	v_and_b32_e32 v4, 7, v4
	v_readlane_b32 s21, v253, 43
	v_lshlrev_b32_e32 v125, 2, v6
	v_and_b32_e32 v6, 56, v8
	v_add_u32_e32 v9, s16, v9
	v_mul_u32_u24_e32 v130, 0x90, v126
	v_and_b32_e32 v8, 24, v8
	v_lshl_add_u32 v141, v4, 4, s16
	v_lshlrev_b32_e32 v4, 3, v4
	v_mul_u32_u24_e32 v11, 0x90, v127
	s_addc_u32 s4, s21, s1
	s_lshl_b32 s5, s5, 4
	v_or_b32_e32 v128, 16, v126
	v_or_b32_e32 v129, 24, v126
	v_cmp_gt_u32_e32 vcc, 16, v5
	v_lshlrev_b32_e32 v110, 1, v6
	v_add_u32_e32 v142, v9, v130
	v_add_u32_e32 v143, v132, v7
	v_add_u32_e32 v144, v10, v8
	v_lshlrev_b32_e32 v112, 1, v4
	v_add_u32_e32 v145, v141, v11
	v_readlane_b32 s26, v255, 40
	s_lshl_b32 s26, s26, 1
	s_bfe_u32 s98, s26, 0x10001
	s_andn2_b32 s26, s26, 3
	s_or_b32 s26, s26, s98
	s_lshl_b32 s16, s26, 7
	s_branch .LBB0_359
.LBB0_358:
	s_or_b64 exec, exec, s[0:1]
	s_add_i32 s26, s26, 2
	s_addk_i32 s16, 0x100
	s_bitcmp0_b32 s26, 1
	s_cbranch_scc1 .LBB0_361

; #define LAS __attribute__((address_space(3)))
; DI float q_norm2(const bf16x8 (&qf)[2]) { float a = sumsq8(qf[0]) + sumsq8(qf[1]); a += __shfl_xor(a, 16); a += __shfl_xor(a, 32); return a; }
; DI float d_stage_rpb(const float* rpb_l, int h, LAS char* vt, int lane) {
;     LAS float* rp = (LAS float*)(vt + 12288); float rmax = 0.f;
;     for (int i = lane; i < 15 * 31; i += 64) { const float v = rpb_l[h * 465 + i] * LOG2E; rp[i] = v; rmax = fmaxf(rmax, fabsf(v)); }
; #pragma unroll
;     for (int o_ = 1; o_ < 64; o_ <<= 1) rmax = fmaxf(rmax, __shfl_xor(rmax, o_));
;     return rmax;
; }
; DI void mixerD2_unit(int u, const bf16* PROJ, bf16* YC, float rmax, const float* kmax_l, LAS char* vt, int wave, int lane) {
;     const int b = u >> 6, h = (u >> 4) & 3, wu = (u & 15) * 8 + wave, rr = wu >> 2, cb = wu & 3, r = lane & 15, g = lane >> 4;
;     const bf16* kb = slab(PROJ, C_DK + h * 64, b); const bf16* vb = slab(PROJ, C_DV + h * 64, b);
;     const int qcol = 16 * cb + r, tq = 64 * rr + qcol;
;     const int cs = min(max(qcol - 8, 0), 48), rs = min(max(rr - 4, 0), 24), c0 = min(max(16 * cb - 8, 0), 32);
;     LAS float* rp = (LAS float*)(vt + 12288);
;     bf16x8 qf[2];
; #pragma unroll
;     for (int ks = 0; ks < 2; ++ks) qf[ks] = *(const bf16x8*)(slab(PROJ, C_DQ + h * 64, b) + (size_t)tq * 64 + 32 * ks + 8 * g);
;     const float bound = sqrtf(q_norm2(qf) * (kmax_l[b * 128 + 104 + 2 * h] + kmax_l[b * 128 + 105 + 2 * h])) * 1.01f + 0.05f + rmax;
;     const f32x4 cinit = {-bound, -bound, -bound, -bound};
;     f32x4 o[4], ol = {0.f, 0.f, 0.f, 0.f};
; #pragma unroll
;     for (int c = 0; c < 4; ++c) o[c] = ol;
;     const int tb0 = 64 * rs + c0, dr0 = rs - rr + 7;
;     const int kc0 = c0 + 4 * g - cs;
;     const LAS float* rpl = rp + dr0 * 31 + (c0 + 4 * g - qcol + 15);
;     TileRegs R0, R1, R2;
;     tile_load(R0, kb, vb, tb0, 1, lane); tile_load(R1, kb, vb, tb0 + 64, 1, lane); tile_load(R2, kb, vb, tb0 + 128, 1, lane);
.LBB0_361:
	v_readlane_b32 s0, v253, 0
	v_mbcnt_lo_u32_b32 v4, -1, 0
	v_mbcnt_hi_u32_b32 v4, -1, v4
	s_and_b64 vcc, exec, s[36:37]
	s_nop 0
	v_add_u32_e32 v5, s0, v4
	s_nop 0
	v_readfirstlane_b32 s0, v5
	s_cbranch_vccnz .LBB0_369
	s_ashr_i32 s2, s0, 6
	v_readlane_b32 s26, v255, 27
	v_readlane_b32 s1, v254, 26
	s_lshl_b32 s0, s2, 14
	s_lshl_b32 s34, s26, 10
	s_add_i32 s20, s0, 0
	s_lshl_b64 s[0:1], s[34:35], 2
	v_readlane_b32 s4, v253, 42
	v_readlane_b32 s5, v253, 43
	s_add_u32 s4, s4, s0
	s_addc_u32 s5, s5, s1
	s_lshl_b32 s0, s2, 4
	s_and_b32 s16, s0, 48
	v_and_b32_e32 v5, 15, v4
	v_sub_u32_e64 v8, s16, 8 clamp
	v_or_b32_e32 v78, s16, v5
	v_readfirstlane_b32 s0, v8
	v_bfe_u32 v6, v4, 4, 2
	v_sub_u32_e64 v7, v78, 8 clamp
	v_and_b32_e32 v10, 64, v224
	s_min_u32 s33, s0, 32
	v_lshlrev_b32_e32 v68, 3, v6
	v_xor_b32_e32 v9, 16, v224
	v_add_u32_e32 v10, 64, v10
	v_min_u32_e32 v7, 48, v7
	v_lshl_add_u32 v6, v6, 2, s33
	v_cmp_lt_i32_e32 vcc, v9, v10
	v_sub_u32_e32 v7, v6, v7
	v_mov_b32_e32 v8, s20
	s_movk_i32 s1, 0x90
	v_cndmask_b32_e32 v9, v224, v9, vcc
	v_mad_u32_u24 v87, v5, s1, v8
	v_add_u32_e32 v5, 1, v7
	v_lshlrev_b32_e32 v79, 2, v9
	v_xor_b32_e32 v9, 32, v224
	v_cmp_gt_u32_e64 s[38:39], 16, v5
	v_add_u32_e32 v5, 2, v7
	v_cmp_lt_i32_e32 vcc, v9, v10
	v_cmp_gt_u32_e64 s[40:41], 16, v5
	v_add_u32_e32 v5, 3, v7
	v_and_b32_e32 v69, 63, v4
	v_cndmask_b32_e32 v9, v224, v9, vcc
	v_cmp_gt_u32_e64 s[42:43], 16, v5
	v_add_u32_e32 v5, 17, v7
	v_lshlrev_b32_e32 v80, 2, v9
	v_sub_u32_e32 v6, v6, v78
	v_lshlrev_b32_e32 v9, 3, v69
	s_movk_i32 s0, 0xffef
	v_cmp_gt_u32_e64 s[46:47], 16, v5
	v_add_u32_e32 v5, 18, v7
	v_lshl_add_u32 v81, v6, 2, s20
	v_and_b32_e32 v6, 56, v9
	v_cmp_gt_u32_e64 s[36:37], 16, v7
	v_cmp_lt_u32_e64 s[44:45], s0, v7
	v_cmp_gt_u32_e64 s[48:49], 16, v5
	v_add_u32_e32 v5, 19, v7
	v_and_b32_e32 v7, 24, v9
	v_xor_b32_e32 v9, 1, v224
	v_cmp_lt_i32_e32 vcc, v9, v10
	v_lshlrev_b32_e32 v11, 4, v4
	v_cmp_gt_u32_e64 s[50:51], 16, v5
	v_cndmask_b32_e32 v9, v224, v9, vcc
	v_lshlrev_b32_e32 v89, 2, v9
	v_xor_b32_e32 v9, 2, v224
	v_cmp_lt_i32_e32 vcc, v9, v10
	v_bfe_u32 v5, v4, 2, 4
	v_bfe_u32 v82, v4, 3, 3
	v_cndmask_b32_e32 v9, v224, v9, vcc
	v_lshlrev_b32_e32 v90, 2, v9
	v_xor_b32_e32 v9, 4, v224
	v_cmp_lt_i32_e32 vcc, v9, v10
	v_and_b32_e32 v11, 0x70, v11
	v_mad_u32_u24 v5, v5, s1, v8
	v_cndmask_b32_e32 v9, v224, v9, vcc
	v_and_b32_e32 v8, 7, v4
	v_lshlrev_b32_e32 v91, 2, v9
	v_xor_b32_e32 v9, 8, v224
	v_readlane_b32 s52, v253, 5
	v_or_b32_e32 v83, 8, v82
	v_add_u32_e32 v11, s20, v11
	v_lshl_add_u32 v88, v8, 4, s20
	v_cmp_lt_i32_e32 vcc, v9, v10
	s_addk_i32 s20, 0x3000
	s_mul_i32 s1, s26, 0x1d10
	v_readlane_b32 s64, v253, 17
	v_readlane_b32 s66, v253, 19
	v_mul_u32_u24_e32 v86, 0x90, v82
	v_and_b32_e32 v12, 48, v4
	v_lshlrev_b32_e32 v4, 3, v8
	v_mul_u32_u24_e32 v8, 0x90, v83
	v_cndmask_b32_e32 v9, v224, v9, vcc
	v_lshl_add_u32 v93, v69, 2, s20
	s_mul_hi_u32 s0, s26, 0x1d10
	v_readlane_b32 s65, v253, 18
	v_readlane_b32 s66, v253, 23
	s_add_u32 s20, s64, s1
	s_mov_b32 s34, -1
	v_or_b32_e32 v84, 16, v82
	v_or_b32_e32 v85, 24, v82
	v_lshlrev_b32_e32 v92, 2, v9
	v_or_b32_e32 v94, 0xffffffc0, v69
	s_addc_u32 s21, s65, s0
	v_mov_b32_e32 v99, 0
	v_lshlrev_b32_e32 v70, 1, v6
	v_add_u32_e32 v95, v11, v86
	v_add_u32_e32 v96, v87, v12
	v_add_u32_e32 v97, v5, v7
	v_lshlrev_b32_e32 v72, 1, v4
	v_add_u32_e32 v98, v88, v8
	v_readlane_b32 s52, v255, 40
	s_lshl_b32 s52, s52, 1
	s_bfe_u32 s98, s52, 0x10001
	s_andn2_b32 s52, s52, 3
	s_or_b32 s52, s52, s98
	v_readlane_b32 s27, v255, 28
	v_readlane_b32 s53, v253, 6
	v_readlane_b32 s54, v253, 7
	v_readlane_b32 s55, v253, 8
	v_readlane_b32 s56, v253, 9
	v_readlane_b32 s57, v253, 10
	v_readlane_b32 s58, v253, 11
	v_readlane_b32 s59, v253, 12
	v_readlane_b32 s60, v253, 13
	v_readlane_b32 s61, v253, 14
	v_readlane_b32 s62, v253, 15
	v_readlane_b32 s63, v253, 16
	v_readlane_b32 s67, v253, 20
	s_branch .LBB0_364
.LBB0_363:
	s_lshl_b32 s0, s52, 3
	s_and_b32 s0, s0, 0x78
	s_ashr_i32 s26, s52, 6
	s_add_i32 s0, s0, s2
	s_ashr_i32 s0, s0, 2
	s_ashr_i32 s27, s26, 31
	s_lshl_b32 s1, s53, 21
	s_add_u32 s1, s10, s1
	s_addc_u32 s55, s11, 0
	s_lshl_b32 s54, s0, 6
	s_max_i32 s57, s0, 4
	s_lshl_b64 s[30:31], s[26:27], 18
	v_or_b32_e32 v4, s54, v78
	s_add_i32 s57, s57, -4
	v_ashrrev_i32_e32 v5, 31, v4
	s_add_u32 s30, s1, s30
	v_lshlrev_b64 v[4:5], 7, v[4:5]
	s_addc_u32 s31, s55, s31
	v_lshl_add_u64 v[4:5], s[30:31], 0, v[4:5]
	v_lshlrev_b32_e32 v188, 1, v68
	v_lshl_add_u64 v[4:5], v[4:5], 0, v[188:189]
	s_mov_b64 s[60:61], 0x6000000
	s_mov_b32 s1, 0x6000000
	v_lshl_add_u64 v[8:9], v[4:5], 0, s[60:61]
	v_add_co_u32_e32 v4, vcc, s1, v4
	s_min_u32 s1, s57, 24
	s_nop 0
	v_addc_co_u32_e32 v5, vcc, 0, v5, vcc
	global_load_dwordx4 v[4:7], v[4:5], off
	s_nop 0
	global_load_dwordx4 v[8:11], v[8:9], off offset:64
	s_lshl_b32 s55, s26, 7
	s_lshl_b32 s57, s53, 1
	s_or_b32 s60, s57, s55
	s_ashr_i32 s61, s60, 31
	s_lshl_b64 s[60:61], s[60:61], 2
	s_add_u32 s60, s4, s60
	s_addc_u32 s61, s5, s61
	global_load_dwordx2 v[12:13], v189, s[60:61] offset:416
	v_mov_b32_e32 v71, v189
	v_lshl_add_u64 v[14:15], s[30:31], 0, v[70:71]
	s_mov_b64 s[60:61], 0x6800000
	s_lshl_b32 s55, s1, 6
	v_lshl_add_u64 v[74:75], v[14:15], 0, s[60:61]
	s_mov_b64 s[60:61], 0x7000000
	s_or_b32 s55, s55, s33
	v_lshl_add_u64 v[76:77], v[14:15], 0, s[60:61]
	v_or_b32_e32 v14, s55, v82
	v_lshlrev_b32_e32 v188, 7, v14
	v_lshl_add_u64 v[14:15], v[74:75], 0, v[188:189]
	v_lshl_add_u64 v[20:21], v[76:77], 0, v[188:189]
	v_add_lshl_u32 v188, s55, v83, 7
	global_load_dwordx4 v[16:19], v[14:15], off
	s_nop 0
	global_load_dwordx4 v[20:23], v[20:21], off
	v_lshl_add_u64 v[14:15], v[74:75], 0, v[188:189]
	v_lshl_add_u64 v[28:29], v[76:77], 0, v[188:189]
	v_add_lshl_u32 v188, s55, v84, 7
	global_load_dwordx4 v[24:27], v[14:15], off
	s_nop 0
	global_load_dwordx4 v[28:31], v[28:29], off
	v_lshl_add_u64 v[14:15], v[74:75], 0, v[188:189]
	v_lshl_add_u64 v[36:37], v[76:77], 0, v[188:189]
	v_add_lshl_u32 v188, s55, v85, 7
	global_load_dwordx4 v[32:35], v[14:15], off
	s_nop 0
	global_load_dwordx4 v[36:39], v[36:37], off
	v_lshl_add_u64 v[14:15], v[74:75], 0, v[188:189]
	v_lshl_add_u64 v[44:45], v[76:77], 0, v[188:189]
	global_load_dwordx4 v[40:43], v[14:15], off
	s_nop 0
	global_load_dwordx4 v[44:47], v[44:45], off
	s_add_i32 s57, s55, 64
	s_sub_i32 s0, s1, s0
	s_mulk_i32 s0, 0x7c
	v_add_u32_e32 v71, s0, v81
	v_add_u32_e32 v73, 0x33a0, v71
	s_or_b32 s54, s54, s16
	s_waitcnt vmcnt(10)
; DI void d_compute(f32x4 (&o)[4], f32x4& ol, const TileRegs& R, const bf16x8 (&qf)[2], const f32x4 cinit, int kr, int kc0, const LAS float* rpl, LAS char* vt, int lane) {
;     tile_v_to_lds(R, vt, lane);
;     const LAS float* rr_ = rpl + kr * 31;
;     f32x4 st[2];
; #pragma unroll
;     for (int t = 0; t < 2; ++t) {
;         st[t] = MFMA16(k_frag(vt, t, 0, lane), qf[0], cinit); st[t] = MFMA16(k_frag(vt, t, 1, lane), qf[1], st[t]);
; #pragma unroll
;         for (int i = 0; i < 4; ++i) { const bool ok = (unsigned)(kc0 + 16 * t + i) <= 15u;
;             const float v = st[t][i] + rr_[16 * t + i];
;             st[t][i] = ok ? v : -1e30f; }
;     }
;     fb_update(o, ol, st[0], st[1], vt, lane);
;     asm volatile("" ::: "memory");
; }
; DI float d_stage_rpb(const float* rpb_l, int h, LAS char* vt, int lane) {
;     LAS float* rp = (LAS float*)(vt + 12288); float rmax = 0.f;
;     for (int i = lane; i < 15 * 31; i += 64) { const float v = rpb_l[h * 465 + i] * LOG2E; rp[i] = v; rmax = fmaxf(rmax, fabsf(v)); }
; #pragma unroll
;     for (int o_ = 1; o_ < 64; o_ <<= 1) rmax = fmaxf(rmax, __shfl_xor(rmax, o_));
;     return rmax;
; }
; DI void mixerD2_unit(int u, const bf16* PROJ, bf16* YC, float rmax, const float* kmax_l, LAS char* vt, int wave, int lane) {
;     const int b = u >> 6, h = (u >> 4) & 3, wu = (u & 15) * 8 + wave, rr = wu >> 2, cb = wu & 3, r = lane & 15, g = lane >> 4;
;     const bf16* kb = slab(PROJ, C_DK + h * 64, b); const bf16* vb = slab(PROJ, C_DV + h * 64, b);
;     const int qcol = 16 * cb + r, tq = 64 * rr + qcol;
;     const int cs = min(max(qcol - 8, 0), 48), rs = min(max(rr - 4, 0), 24), c0 = min(max(16 * cb - 8, 0), 32);
;     LAS float* rp = (LAS float*)(vt + 12288);
;     bf16x8 qf[2];
; #pragma unroll
;     for (int ks = 0; ks < 2; ++ks) qf[ks] = *(const bf16x8*)(slab(PROJ, C_DQ + h * 64, b) + (size_t)tq * 64 + 32 * ks + 8 * g);
;     const float bound = sqrtf(q_norm2(qf) * (kmax_l[b * 128 + 104 + 2 * h] + kmax_l[b * 128 + 105 + 2 * h])) * 1.01f + 0.05f + rmax;
;     const f32x4 cinit = {-bound, -bound, -bound, -bound};
;     f32x4 o[4], ol = {0.f, 0.f, 0.f, 0.f};
; #pragma unroll
;     for (int c = 0; c < 4; ++c) o[c] = ol;
;     const int tb0 = 64 * rs + c0, dr0 = rs - rr + 7;
;     const int kc0 = c0 + 4 * g - cs;
;     const LAS float* rpl = rp + dr0 * 31 + (c0 + 4 * g - qcol + 15);
;     TileRegs R0, R1, R2;
	v_and_b32_e32 v48, 0xffff0000, v4
	s_waitcnt vmcnt(9)
	v_and_b32_e32 v49, 0xffff0000, v8
	v_and_b32_e32 v53, 0xffff0000, v9
	v_and_b32_e32 v52, 0xffff0000, v5
	v_lshlrev_b32_e32 v14, 16, v4
	v_lshlrev_b32_e32 v15, 16, v8
	v_lshlrev_b32_e32 v50, 16, v5
	v_lshlrev_b32_e32 v51, 16, v9
	v_and_b32_e32 v57, 0xffff0000, v10
	v_and_b32_e32 v56, 0xffff0000, v6
	v_pk_mul_f32 v[48:49], v[48:49], v[48:49]
	v_pk_mul_f32 v[52:53], v[52:53], v[52:53]
	v_lshlrev_b32_e32 v54, 16, v6
	v_lshlrev_b32_e32 v55, 16, v10
	v_and_b32_e32 v61, 0xffff0000, v11
	v_and_b32_e32 v60, 0xffff0000, v7
	v_pk_mul_f32 v[56:57], v[56:57], v[56:57]
	v_pk_fma_f32 v[14:15], v[14:15], v[14:15], v[48:49]
	v_pk_fma_f32 v[48:49], v[50:51], v[50:51], v[52:53]
	v_lshlrev_b32_e32 v58, 16, v7
	v_lshlrev_b32_e32 v59, 16, v11
	v_pk_mul_f32 v[60:61], v[60:61], v[60:61]
	v_pk_fma_f32 v[50:51], v[54:55], v[54:55], v[56:57]
	v_pk_add_f32 v[14:15], v[14:15], v[48:49]
	v_pk_fma_f32 v[52:53], v[58:59], v[58:59], v[60:61]
	v_pk_add_f32 v[14:15], v[50:51], v[14:15]
	s_waitcnt vmcnt(8)
	v_mov_b32_e32 v48, v13
	v_pk_add_f32 v[14:15], v[52:53], v[14:15]
	s_nop 0
	v_add_f32_e32 v14, v14, v15
	ds_bpermute_b32 v15, v79, v14
	s_waitcnt lgkmcnt(0)
	v_add_f32_e32 v15, v14, v15
	ds_bpermute_b32 v49, v80, v15
	v_mov_b32_e32 v14, v12
	s_waitcnt lgkmcnt(0)
	v_pk_add_f32 v[12:13], v[14:15], v[48:49]
	s_nop 0
	v_mul_f32_e32 v12, v12, v13
	v_mul_f32_e32 v13, 0x4f800000, v12
	v_cmp_gt_f32_e32 vcc, s92, v12
	v_or_b32_e32 v14, s57, v82
	v_lshlrev_b32_e32 v188, 7, v14
	v_cndmask_b32_e32 v12, v12, v13, vcc
	v_sqrt_f32_e32 v13, v12
	v_lshl_add_u64 v[48:49], v[74:75], 0, v[188:189]
	v_lshl_add_u64 v[52:53], v[76:77], 0, v[188:189]
	v_add_lshl_u32 v188, s57, v83, 7
	v_add_u32_e32 v14, -1, v13
	v_lshl_add_u64 v[56:57], v[74:75], 0, v[188:189]
	v_lshl_add_u64 v[60:61], v[76:77], 0, v[188:189]
	v_add_lshl_u32 v188, s57, v84, 7
	v_add_u32_e32 v15, 1, v13
	v_fma_f32 v50, -v14, v13, v12
	v_lshl_add_u64 v[64:65], v[74:75], 0, v[188:189]
	v_lshl_add_u64 v[100:101], v[76:77], 0, v[188:189]
	v_add_lshl_u32 v188, s57, v85, 7
	v_fma_f32 v51, -v15, v13, v12
	v_cmp_ge_f32_e64 s[0:1], 0, v50
	v_lshl_add_u64 v[104:105], v[74:75], 0, v[188:189]
	v_lshl_add_u64 v[108:109], v[76:77], 0, v[188:189]
	v_cndmask_b32_e64 v13, v13, v14, s[0:1]
	v_cmp_lt_f32_e64 s[0:1], 0, v51
	global_load_dwordx4 v[48:51], v[48:49], off
	s_nop 0
	global_load_dwordx4 v[52:55], v[52:53], off
	s_nop 0
	global_load_dwordx4 v[56:59], v[56:57], off
	s_nop 0
	global_load_dwordx4 v[60:63], v[60:61], off
	s_nop 0
	global_load_dwordx4 v[64:67], v[64:65], off
	s_nop 0
	global_load_dwordx4 v[100:103], v[100:101], off
	s_nop 0
	global_load_dwordx4 v[104:107], v[104:105], off
	s_nop 0
	global_load_dwordx4 v[108:111], v[108:109], off
	s_waitcnt vmcnt(14)
	ds_write_b128 v95, v[20:23]
	ds_write_b128 v95, v[16:19] offset:4608
	s_waitcnt vmcnt(12)
	ds_write_b128 v95, v[28:31] offset:1152
	ds_write_b128 v95, v[24:27] offset:5760
	s_waitcnt vmcnt(10)
	ds_write_b128 v95, v[36:39] offset:2304
	ds_write_b128 v95, v[32:35] offset:6912
	s_waitcnt vmcnt(8)
	ds_write_b128 v95, v[44:47] offset:3456
	ds_write_b128 v95, v[40:43] offset:8064
	ds_read_b128 v[16:19], v96 offset:4608
	ds_read_b128 v[36:39], v96 offset:4672
	v_cndmask_b32_e64 v13, v13, v15, s[0:1]
	v_mul_f32_e32 v14, 0x37800000, v13
	v_cndmask_b32_e32 v13, v13, v14, vcc
	v_cmp_class_f32_e32 vcc, v12, v226
	s_add_i32 s0, s55, 0x80
	v_or_b32_e32 v112, s0, v82
	v_cndmask_b32_e32 v12, v13, v12, vcc
	v_fmamk_f32 v12, v12, 0x3f8147ae, v227
	v_add_f32_e32 v12, v99, v12
	v_xor_b32_e32 v12, 0x80000000, v12
	v_mov_b32_e32 v13, v12
	v_mov_b32_e32 v14, v12
	v_mov_b32_e32 v15, v12
	v_lshlrev_b32_e32 v188, 7, v112
	v_lshl_add_u64 v[20:21], v[74:75], 0, v[188:189]
	s_waitcnt lgkmcnt(1)
	v_mfma_f32_16x16x32_bf16 v[16:19], v[16:19], v[4:7], v[12:15]
	v_lshl_add_u64 v[24:25], v[76:77], 0, v[188:189]
	v_add_lshl_u32 v188, s0, v83, 7
	v_lshl_add_u64 v[28:29], v[74:75], 0, v[188:189]
	v_lshl_add_u64 v[32:33], v[76:77], 0, v[188:189]
	global_load_dwordx4 v[20:23], v[20:21], off
	s_nop 0
	global_load_dwordx4 v[24:27], v[24:25], off
	s_nop 0
	global_load_dwordx4 v[28:31], v[28:29], off
	s_nop 0
	global_load_dwordx4 v[32:35], v[32:33], off
	ds_read2_b32 v[40:41], v73 offset1:1
	s_waitcnt lgkmcnt(1)
	v_mfma_f32_16x16x32_bf16 v[16:19], v[36:39], v[8:11], v[16:19]
	v_add_u32_e32 v44, 0x33e0, v71
	v_add_u32_e32 v45, 0x33e8, v71
	v_add_lshl_u32 v188, s0, v84, 7
	s_waitcnt lgkmcnt(0)
	s_nop 3
	v_add_f32_e32 v16, v16, v40
	v_cndmask_b32_e64 v73, v234, v16, s[36:37]
	v_add_f32_e32 v16, v17, v41
	v_cndmask_b32_e64 v114, v234, v16, s[38:39]
	v_add_u32_e32 v16, 0x33a8, v71
	ds_read_b128 v[36:39], v96 offset:6912
	ds_read2_b32 v[16:17], v16 offset1:1
	ds_read_b128 v[40:43], v96 offset:6976
	s_waitcnt lgkmcnt(2)
	v_mfma_f32_16x16x32_bf16 v[36:39], v[36:39], v[4:7], v[12:15]
	s_waitcnt lgkmcnt(1)
	v_add_f32_e32 v16, v18, v16
	v_cndmask_b32_e64 v115, v234, v16, s[40:41]
	v_add_f32_e32 v16, v19, v17
	v_cndmask_b32_e64 v116, v234, v16, s[42:43]
	s_waitcnt lgkmcnt(0)
	v_mfma_f32_16x16x32_bf16 v[16:19], v[40:43], v[8:11], v[36:39]
	ds_read2_b32 v[46:47], v44 offset1:1
	ds_read2_b32 v[112:113], v45 offset1:1
	ds_read_b64_tr_b16 v[44:45], v97
	v_exp_f32_e32 v36, v73
	v_exp_f32_e32 v37, v115
	s_waitcnt lgkmcnt(2)
	s_nop 1
	v_add_f32_e32 v16, v16, v46
	v_add_f32_e32 v17, v17, v47
	ds_read_b64_tr_b16 v[46:47], v97 offset:2304
	s_waitcnt lgkmcnt(2)
; DI void d_compute(f32x4 (&o)[4], f32x4& ol, const TileRegs& R, const bf16x8 (&qf)[2], const f32x4 cinit, int kr, int kc0, const LAS float* rpl, LAS char* vt, int lane) {
;     tile_v_to_lds(R, vt, lane);
;     const LAS float* rr_ = rpl + kr * 31;
;     f32x4 st[2];
; #pragma unroll
;     for (int t = 0; t < 2; ++t) {
;         st[t] = MFMA16(k_frag(vt, t, 0, lane), qf[0], cinit); st[t] = MFMA16(k_frag(vt, t, 1, lane), qf[1], st[t]);
; #pragma unroll
;         for (int i = 0; i < 4; ++i) { const bool ok = (unsigned)(kc0 + 16 * t + i) <= 15u;
;             const float v = st[t][i] + rr_[16 * t + i];
;             st[t][i] = ok ? v : -1e30f; }
;     }
;     fb_update(o, ol, st[0], st[1], vt, lane);
;     asm volatile("" ::: "memory");
; }
; DI float d_stage_rpb(const float* rpb_l, int h, LAS char* vt, int lane) {
;     LAS float* rp = (LAS float*)(vt + 12288); float rmax = 0.f;
;     for (int i = lane; i < 15 * 31; i += 64) { const float v = rpb_l[h * 465 + i] * LOG2E; rp[i] = v; rmax = fmaxf(rmax, fabsf(v)); }
; #pragma unroll
;     for (int o_ = 1; o_ < 64; o_ <<= 1) rmax = fmaxf(rmax, __shfl_xor(rmax, o_));
;     return rmax;
; }
; DI void mixerD2_unit(int u, const bf16* PROJ, bf16* YC, float rmax, const float* kmax_l, LAS char* vt, int wave, int lane) {
;     const int b = u >> 6, h = (u >> 4) & 3, wu = (u & 15) * 8 + wave, rr = wu >> 2, cb = wu & 3, r = lane & 15, g = lane >> 4;
;     const bf16* kb = slab(PROJ, C_DK + h * 64, b); const bf16* vb = slab(PROJ, C_DV + h * 64, b);
;     const int qcol = 16 * cb + r, tq = 64 * rr + qcol;
;     const int cs = min(max(qcol - 8, 0), 48), rs = min(max(rr - 4, 0), 24), c0 = min(max(16 * cb - 8, 0), 32);
;     LAS float* rp = (LAS float*)(vt + 12288);
;     bf16x8 qf[2];
; #pragma unroll
;     for (int ks = 0; ks < 2; ++ks) qf[ks] = *(const bf16x8*)(slab(PROJ, C_DQ + h * 64, b) + (size_t)tq * 64 + 32 * ks + 8 * g);
;     const float bound = sqrtf(q_norm2(qf) * (kmax_l[b * 128 + 104 + 2 * h] + kmax_l[b * 128 + 105 + 2 * h])) * 1.01f + 0.05f + rmax;
;     const f32x4 cinit = {-bound, -bound, -bound, -bound};
;     f32x4 o[4], ol = {0.f, 0.f, 0.f, 0.f};
; #pragma unroll
;     for (int c = 0; c < 4; ++c) o[c] = ol;
;     const int tb0 = 64 * rs + c0, dr0 = rs - rr + 7;
;     const int kc0 = c0 + 4 * g - cs;
;     const LAS float* rpl = rp + dr0 * 31 + (c0 + 4 * g - qcol + 15);
;     TileRegs R0, R1, R2;
	v_add_f32_e32 v18, v18, v112
	v_add_f32_e32 v19, v19, v113
	v_cndmask_b32_e64 v16, v234, v16, s[44:45]
	v_cndmask_b32_e64 v17, v234, v17, s[46:47]
	v_cndmask_b32_e64 v18, v234, v18, s[48:49]
	v_cndmask_b32_e64 v19, v234, v19, s[50:51]
	v_exp_f32_e32 v38, v16
	v_exp_f32_e32 v16, v114
	v_exp_f32_e32 v39, v17
	v_exp_f32_e32 v40, v18
	v_exp_f32_e32 v41, v116
	v_exp_f32_e32 v42, v19
	v_cvt_pk_bf16_f32 v36, v36, v16
	v_cvt_pk_bf16_f32 v38, v38, v39
	v_cvt_pk_bf16_f32 v37, v37, v41
	v_cvt_pk_bf16_f32 v39, v40, v42
	ds_read_b64_tr_b16 v[112:113], v97 offset:32
	ds_read_b64_tr_b16 v[114:115], v97 offset:2336
	s_waitcnt lgkmcnt(2)
	v_mfma_f32_16x16x32_bf16 v[124:127], v[44:47], v[36:39], 0
	v_lshl_add_u64 v[44:45], v[74:75], 0, v[188:189]
	v_lshl_add_u64 v[46:47], v[76:77], 0, v[188:189]
	v_add_lshl_u32 v188, s0, v85, 7
	ds_read_b64_tr_b16 v[116:117], v97 offset:64
	ds_read_b64_tr_b16 v[120:121], v97 offset:96
	ds_read_b64_tr_b16 v[118:119], v97 offset:2368
	ds_read_b64_tr_b16 v[122:123], v97 offset:2400
	global_load_dwordx4 v[128:131], v[44:45], off
	global_load_dwordx4 v[132:135], v[46:47], off
	v_lshl_add_u64 v[44:45], v[74:75], 0, v[188:189]
	v_lshl_add_u64 v[46:47], v[76:77], 0, v[188:189]
	global_load_dwordx4 v[136:139], v[44:45], off
	global_load_dwordx4 v[140:143], v[46:47], off
	s_waitcnt vmcnt(14)
	ds_write_b128 v95, v[52:55]
	ds_write_b128 v95, v[48:51] offset:4608
	s_waitcnt vmcnt(12)
	ds_write_b128 v95, v[60:63] offset:1152
	ds_write_b128 v95, v[56:59] offset:5760
	s_waitcnt vmcnt(10)
	ds_write_b128 v95, v[100:103] offset:2304
	ds_write_b128 v95, v[64:67] offset:6912
	s_waitcnt vmcnt(8)
	ds_write_b128 v95, v[108:111] offset:3456
	ds_write_b128 v95, v[104:107] offset:8064
	ds_read_b128 v[48:51], v96 offset:4608
	ds_read_b128 v[56:59], v96 offset:4672
	v_mov_b64_e32 v[16:17], s[84:85]
	v_mov_b64_e32 v[18:19], s[86:87]
	s_add_i32 s0, s55, 0xc0
	s_waitcnt lgkmcnt(14)
	v_mfma_f32_16x16x32_bf16 v[112:115], v[112:115], v[36:39], 0
	v_add_u32_e32 v64, 0x341c, v71
	v_add_u32_e32 v65, 0x345c, v71
	v_add_u32_e32 v66, 0x3464, v71
	v_mfma_f32_16x16x32_bf16 v[40:43], v[16:19], v[36:39], 0
	s_waitcnt lgkmcnt(11)
	v_mfma_f32_16x16x32_bf16 v[116:119], v[116:119], v[36:39], 0
	s_waitcnt lgkmcnt(10)
	v_mfma_f32_16x16x32_bf16 v[120:123], v[120:123], v[36:39], 0
	v_or_b32_e32 v36, s0, v82
	v_lshlrev_b32_e32 v188, 7, v36
	v_lshl_add_u64 v[36:37], v[74:75], 0, v[188:189]
	s_waitcnt lgkmcnt(1)
	v_mfma_f32_16x16x32_bf16 v[48:51], v[48:51], v[4:7], v[12:15]
	v_lshl_add_u64 v[44:45], v[76:77], 0, v[188:189]
	v_add_lshl_u32 v188, s0, v83, 7
	v_lshl_add_u64 v[52:53], v[74:75], 0, v[188:189]
	v_lshl_add_u64 v[60:61], v[76:77], 0, v[188:189]
	global_load_dwordx4 v[36:39], v[36:37], off
	s_nop 0
	global_load_dwordx4 v[44:47], v[44:45], off
	s_nop 0
	global_load_dwordx4 v[52:55], v[52:53], off
	s_nop 0
	global_load_dwordx4 v[60:63], v[60:61], off
	s_waitcnt lgkmcnt(0)
	v_mfma_f32_16x16x32_bf16 v[48:51], v[56:59], v[8:11], v[48:51]
	ds_read2_b32 v[100:101], v64 offset1:1
	ds_read_b128 v[56:59], v96 offset:6912
	v_add_u32_e32 v64, 0x3424, v71
	ds_read2_b32 v[102:103], v64 offset1:1
	ds_read2_b32 v[104:105], v65 offset1:1
	ds_read2_b32 v[106:107], v66 offset1:1
	ds_read_b128 v[64:67], v96 offset:6976
	s_waitcnt lgkmcnt(5)
	v_add_f32_e32 v48, v48, v100
	s_waitcnt lgkmcnt(4)
	v_mfma_f32_16x16x32_bf16 v[56:59], v[56:59], v[4:7], v[12:15]
	v_cndmask_b32_e64 v73, v234, v48, s[36:37]
	v_add_f32_e32 v48, v49, v101
	v_cndmask_b32_e64 v100, v234, v48, s[38:39]
	s_waitcnt lgkmcnt(3)
	v_add_f32_e32 v48, v50, v102
	v_cndmask_b32_e64 v101, v234, v48, s[40:41]
	v_add_f32_e32 v48, v51, v103
	v_cndmask_b32_e64 v102, v234, v48, s[42:43]
	s_waitcnt lgkmcnt(0)
	v_mfma_f32_16x16x32_bf16 v[48:51], v[64:67], v[8:11], v[56:59]
	v_add_lshl_u32 v188, s0, v84, 7
	s_nop 1
	v_exp_f32_e32 v56, v73
	v_exp_f32_e32 v59, v102
	s_nop 2
	v_add_f32_e32 v48, v48, v104
	v_add_f32_e32 v49, v49, v105
	v_cndmask_b32_e64 v48, v234, v48, s[44:45]
	v_cndmask_b32_e64 v49, v234, v49, s[46:47]
	v_exp_f32_e32 v57, v48
	v_exp_f32_e32 v48, v100
	v_exp_f32_e32 v58, v49
	v_exp_f32_e32 v49, v101
	v_add_f32_e32 v50, v50, v106
	v_add_f32_e32 v51, v51, v107
	v_cndmask_b32_e64 v50, v234, v50, s[48:49]
	v_cndmask_b32_e64 v51, v234, v51, s[50:51]
	v_exp_f32_e32 v64, v50
	v_exp_f32_e32 v51, v51
	v_cvt_pk_bf16_f32 v48, v56, v48
	v_cvt_pk_bf16_f32 v49, v49, v59
	v_cvt_pk_bf16_f32 v50, v57, v58
	ds_read_b64_tr_b16 v[58:59], v97 offset:2304
	ds_read_b64_tr_b16 v[56:57], v97
	v_cvt_pk_bf16_f32 v51, v64, v51
	v_add_u32_e32 v73, 0x3590, v71
	s_nop 0
	v_mfma_f32_16x16x32_bf16 v[100:103], v[16:19], v[48:51], v[40:43]
	s_nop 2
	ds_read_b64_tr_b16 v[42:43], v97 offset:2336
	ds_read_b64_tr_b16 v[40:41], v97 offset:32
	ds_read_b64_tr_b16 v[64:65], v97 offset:64
	ds_read_b64_tr_b16 v[104:105], v97 offset:96
	ds_read_b64_tr_b16 v[66:67], v97 offset:2368
	ds_read_b64_tr_b16 v[106:107], v97 offset:2400
	s_waitcnt lgkmcnt(6)
	v_mfma_f32_16x16x32_bf16 v[108:111], v[56:59], v[48:51], v[124:127]
	v_lshl_add_u64 v[56:57], v[74:75], 0, v[188:189]
	v_lshl_add_u64 v[58:59], v[76:77], 0, v[188:189]
	v_add_lshl_u32 v188, s0, v85, 7
	s_waitcnt lgkmcnt(4)
	v_mfma_f32_16x16x32_bf16 v[112:115], v[40:43], v[48:51], v[112:115]
	v_lshl_add_u64 v[40:41], v[74:75], 0, v[188:189]
	global_load_dwordx4 v[124:127], v[56:57], off
	global_load_dwordx4 v[144:147], v[58:59], off
	v_lshl_add_u64 v[42:43], v[76:77], 0, v[188:189]
	global_load_dwordx4 v[148:151], v[40:41], off
	global_load_dwordx4 v[152:155], v[42:43], off
	s_waitcnt vmcnt(14)
	ds_write_b128 v95, v[24:27]
	ds_write_b128 v95, v[20:23] offset:4608
	s_waitcnt vmcnt(12)
; DI void d_compute(f32x4 (&o)[4], f32x4& ol, const TileRegs& R, const bf16x8 (&qf)[2], const f32x4 cinit, int kr, int kc0, const LAS float* rpl, LAS char* vt, int lane) {
;     tile_v_to_lds(R, vt, lane);
;     const LAS float* rr_ = rpl + kr * 31;
;     f32x4 st[2];
; #pragma unroll
;     for (int t = 0; t < 2; ++t) {
;         st[t] = MFMA16(k_frag(vt, t, 0, lane), qf[0], cinit); st[t] = MFMA16(k_frag(vt, t, 1, lane), qf[1], st[t]);
; #pragma unroll
;         for (int i = 0; i < 4; ++i) { const bool ok = (unsigned)(kc0 + 16 * t + i) <= 15u;
;             const float v = st[t][i] + rr_[16 * t + i];
;             st[t][i] = ok ? v : -1e30f; }
;     }
;     fb_update(o, ol, st[0], st[1], vt, lane);
;     asm volatile("" ::: "memory");
; }
; DI float d_stage_rpb(const float* rpb_l, int h, LAS char* vt, int lane) {
;     LAS float* rp = (LAS float*)(vt + 12288); float rmax = 0.f;
;     for (int i = lane; i < 15 * 31; i += 64) { const float v = rpb_l[h * 465 + i] * LOG2E; rp[i] = v; rmax = fmaxf(rmax, fabsf(v)); }
; #pragma unroll
;     for (int o_ = 1; o_ < 64; o_ <<= 1) rmax = fmaxf(rmax, __shfl_xor(rmax, o_));
;     return rmax;
; }
; DI void mixerD2_unit(int u, const bf16* PROJ, bf16* YC, float rmax, const float* kmax_l, LAS char* vt, int wave, int lane) {
;     const int b = u >> 6, h = (u >> 4) & 3, wu = (u & 15) * 8 + wave, rr = wu >> 2, cb = wu & 3, r = lane & 15, g = lane >> 4;
;     const bf16* kb = slab(PROJ, C_DK + h * 64, b); const bf16* vb = slab(PROJ, C_DV + h * 64, b);
;     const int qcol = 16 * cb + r, tq = 64 * rr + qcol;
;     const int cs = min(max(qcol - 8, 0), 48), rs = min(max(rr - 4, 0), 24), c0 = min(max(16 * cb - 8, 0), 32);
;     LAS float* rp = (LAS float*)(vt + 12288);
;     bf16x8 qf[2];
; #pragma unroll
;     for (int ks = 0; ks < 2; ++ks) qf[ks] = *(const bf16x8*)(slab(PROJ, C_DQ + h * 64, b) + (size_t)tq * 64 + 32 * ks + 8 * g);
;     const float bound = sqrtf(q_norm2(qf) * (kmax_l[b * 128 + 104 + 2 * h] + kmax_l[b * 128 + 105 + 2 * h])) * 1.01f + 0.05f + rmax;
;     const f32x4 cinit = {-bound, -bound, -bound, -bound};
;     f32x4 o[4], ol = {0.f, 0.f, 0.f, 0.f};
; #pragma unroll
;     for (int c = 0; c < 4; ++c) o[c] = ol;
;     const int tb0 = 64 * rs + c0, dr0 = rs - rr + 7;
;     const int kc0 = c0 + 4 * g - cs;
;     const LAS float* rpl = rp + dr0 * 31 + (c0 + 4 * g - qcol + 15);
;     TileRegs R0, R1, R2;
	ds_write_b128 v95, v[32:35] offset:1152
	ds_write_b128 v95, v[28:31] offset:5760
	s_waitcnt vmcnt(10)
	ds_write_b128 v95, v[132:135] offset:2304
	ds_write_b128 v95, v[128:131] offset:6912
	s_waitcnt vmcnt(8)
	ds_write_b128 v95, v[140:143] offset:3456
	ds_write_b128 v95, v[136:139] offset:8064
	ds_read_b128 v[20:23], v96 offset:4608
	ds_read_b128 v[24:27], v96 offset:4672
	s_add_i32 s0, s55, 0x100
	v_or_b32_e32 v40, s0, v82
	v_lshlrev_b32_e32 v188, 7, v40
	s_waitcnt lgkmcnt(1)
	v_mfma_f32_16x16x32_bf16 v[20:23], v[20:23], v[4:7], v[12:15]
	v_lshl_add_u64 v[28:29], v[74:75], 0, v[188:189]
	v_lshl_add_u64 v[30:31], v[76:77], 0, v[188:189]
	v_add_lshl_u32 v188, s0, v83, 7
	v_mfma_f32_16x16x32_bf16 v[116:119], v[64:67], v[48:51], v[116:119]
	v_mfma_f32_16x16x32_bf16 v[104:107], v[104:107], v[48:51], v[120:123]
	global_load_dwordx4 v[40:43], v[28:29], off
	global_load_dwordx4 v[48:51], v[30:31], off
	v_lshl_add_u64 v[28:29], v[74:75], 0, v[188:189]
	v_lshl_add_u64 v[30:31], v[76:77], 0, v[188:189]
	global_load_dwordx4 v[56:59], v[28:29], off
	global_load_dwordx4 v[64:67], v[30:31], off
	v_add_u32_e32 v28, 0x3498, v71
	s_waitcnt lgkmcnt(0)
	v_mfma_f32_16x16x32_bf16 v[20:23], v[24:27], v[8:11], v[20:23]
	ds_read2_b32 v[32:33], v28 offset1:1
	ds_read_b128 v[24:27], v96 offset:6912
	v_add_u32_e32 v28, 0x34a0, v71
	v_add_u32_e32 v29, 0x34d8, v71
	v_add_u32_e32 v30, 0x34e0, v71
	ds_read2_b32 v[34:35], v28 offset1:1
	ds_read2_b32 v[120:121], v29 offset1:1
	ds_read2_b32 v[122:123], v30 offset1:1
	ds_read_b128 v[28:31], v96 offset:6976
	s_waitcnt lgkmcnt(5)
	v_add_f32_e32 v20, v20, v32
	s_waitcnt lgkmcnt(4)
	v_mfma_f32_16x16x32_bf16 v[24:27], v[24:27], v[4:7], v[12:15]
	v_cndmask_b32_e64 v32, v234, v20, s[36:37]
	v_add_f32_e32 v20, v21, v33
	v_cndmask_b32_e64 v33, v234, v20, s[38:39]
	s_waitcnt lgkmcnt(3)
	v_add_f32_e32 v20, v22, v34
	v_cndmask_b32_e64 v34, v234, v20, s[40:41]
	v_add_f32_e32 v20, v23, v35
	v_cndmask_b32_e64 v35, v234, v20, s[42:43]
	s_waitcnt lgkmcnt(0)
	v_mfma_f32_16x16x32_bf16 v[20:23], v[28:31], v[8:11], v[24:27]
	v_add_lshl_u32 v188, s0, v84, 7
	s_nop 1
	v_exp_f32_e32 v24, v32
	v_exp_f32_e32 v27, v35
	s_nop 2
	v_add_f32_e32 v20, v20, v120
	v_add_f32_e32 v21, v21, v121
	v_cndmask_b32_e64 v20, v234, v20, s[44:45]
	v_cndmask_b32_e64 v21, v234, v21, s[46:47]
	v_exp_f32_e32 v25, v20
	v_exp_f32_e32 v20, v33
	v_exp_f32_e32 v26, v21
	v_exp_f32_e32 v21, v34
	v_add_f32_e32 v22, v22, v122
	v_add_f32_e32 v23, v23, v123
	v_cndmask_b32_e64 v22, v234, v22, s[48:49]
	v_cndmask_b32_e64 v23, v234, v23, s[50:51]
	v_exp_f32_e32 v28, v22
	v_exp_f32_e32 v23, v23
	v_cvt_pk_bf16_f32 v20, v24, v20
	v_cvt_pk_bf16_f32 v21, v21, v27
	v_cvt_pk_bf16_f32 v22, v25, v26
	ds_read_b64_tr_b16 v[26:27], v97 offset:2304
	ds_read_b64_tr_b16 v[24:25], v97
	v_cvt_pk_bf16_f32 v23, v28, v23
	ds_read_b64_tr_b16 v[30:31], v97 offset:2336
	ds_read_b64_tr_b16 v[28:29], v97 offset:32
	ds_read_b64_tr_b16 v[32:33], v97 offset:64
	ds_read_b64_tr_b16 v[120:121], v97 offset:96
	ds_read_b64_tr_b16 v[34:35], v97 offset:2368
	ds_read_b64_tr_b16 v[122:123], v97 offset:2400
	s_waitcnt lgkmcnt(6)
	v_mfma_f32_16x16x32_bf16 v[108:111], v[24:27], v[20:23], v[108:111]
	v_lshl_add_u64 v[24:25], v[74:75], 0, v[188:189]
	v_lshl_add_u64 v[26:27], v[76:77], 0, v[188:189]
	v_add_lshl_u32 v188, s0, v85, 7
	global_load_dwordx4 v[128:131], v[24:25], off
	global_load_dwordx4 v[132:135], v[26:27], off
	v_lshl_add_u64 v[24:25], v[74:75], 0, v[188:189]
	v_lshl_add_u64 v[26:27], v[76:77], 0, v[188:189]
	global_load_dwordx4 v[136:139], v[24:25], off
	global_load_dwordx4 v[140:143], v[26:27], off
	s_waitcnt vmcnt(14)
	ds_write_b128 v95, v[44:47]
	ds_write_b128 v95, v[36:39] offset:4608
	s_waitcnt vmcnt(12)
	ds_write_b128 v95, v[60:63] offset:1152
	ds_write_b128 v95, v[52:55] offset:5760
	s_waitcnt vmcnt(10)
	ds_write_b128 v95, v[144:147] offset:2304
	ds_write_b128 v95, v[124:127] offset:6912
	s_waitcnt vmcnt(8)
	ds_write_b128 v95, v[152:155] offset:3456
	ds_write_b128 v95, v[148:151] offset:8064
	s_waitcnt lgkmcnt(12)
	v_mfma_f32_16x16x32_bf16 v[112:115], v[28:31], v[20:23], v[112:115]
	ds_read_b128 v[28:31], v96 offset:4608
	ds_read_b128 v[36:39], v96 offset:4672
	s_add_i32 s0, s55, 0x140
	v_mfma_f32_16x16x32_bf16 v[100:103], v[16:19], v[20:23], v[100:103]
	v_add_u32_e32 v52, 0x3514, v71
	v_add_u32_e32 v53, 0x3554, v71
	v_add_u32_e32 v54, 0x355c, v71
	s_waitcnt lgkmcnt(11)
	v_mfma_f32_16x16x32_bf16 v[116:119], v[32:35], v[20:23], v[116:119]
	s_waitcnt lgkmcnt(10)
	v_mfma_f32_16x16x32_bf16 v[104:107], v[120:123], v[20:23], v[104:107]
	v_or_b32_e32 v20, s0, v82
	v_lshlrev_b32_e32 v188, 7, v20
	v_lshl_add_u64 v[20:21], v[74:75], 0, v[188:189]
	s_waitcnt lgkmcnt(1)
	v_mfma_f32_16x16x32_bf16 v[44:47], v[28:31], v[4:7], v[12:15]
	v_lshl_add_u64 v[24:25], v[76:77], 0, v[188:189]
	v_add_lshl_u32 v188, s0, v83, 7
	v_lshl_add_u64 v[32:33], v[74:75], 0, v[188:189]
	v_lshl_add_u64 v[34:35], v[76:77], 0, v[188:189]
	global_load_dwordx4 v[20:23], v[20:21], off
	s_nop 0
	global_load_dwordx4 v[24:27], v[24:25], off
	s_nop 0
	global_load_dwordx4 v[28:31], v[32:33], off
	s_nop 0
	global_load_dwordx4 v[32:35], v[34:35], off
	s_waitcnt lgkmcnt(0)
	v_mfma_f32_16x16x32_bf16 v[36:39], v[36:39], v[8:11], v[44:47]
	ds_read2_b32 v[60:61], v52 offset1:1
	v_add_lshl_u32 v188, s0, v84, 7
	s_nop 0
	ds_read_b128 v[44:47], v96 offset:6912
	v_add_u32_e32 v52, 0x351c, v71
	ds_read2_b32 v[62:63], v52 offset1:1
	ds_read2_b32 v[120:121], v53 offset1:1
	ds_read2_b32 v[122:123], v54 offset1:1
	ds_read_b128 v[52:55], v96 offset:6976
	s_waitcnt lgkmcnt(5)
	v_add_f32_e32 v36, v36, v60
	s_waitcnt lgkmcnt(4)
; DI void d_compute(f32x4 (&o)[4], f32x4& ol, const TileRegs& R, const bf16x8 (&qf)[2], const f32x4 cinit, int kr, int kc0, const LAS float* rpl, LAS char* vt, int lane) {
;     tile_v_to_lds(R, vt, lane);
;     const LAS float* rr_ = rpl + kr * 31;
;     f32x4 st[2];
; #pragma unroll
;     for (int t = 0; t < 2; ++t) {
;         st[t] = MFMA16(k_frag(vt, t, 0, lane), qf[0], cinit); st[t] = MFMA16(k_frag(vt, t, 1, lane), qf[1], st[t]);
; #pragma unroll
;         for (int i = 0; i < 4; ++i) { const bool ok = (unsigned)(kc0 + 16 * t + i) <= 15u;
;             const float v = st[t][i] + rr_[16 * t + i];
;             st[t][i] = ok ? v : -1e30f; }
;     }
;     fb_update(o, ol, st[0], st[1], vt, lane);
;     asm volatile("" ::: "memory");
; }
; DI float d_stage_rpb(const float* rpb_l, int h, LAS char* vt, int lane) {
;     LAS float* rp = (LAS float*)(vt + 12288); float rmax = 0.f;
;     for (int i = lane; i < 15 * 31; i += 64) { const float v = rpb_l[h * 465 + i] * LOG2E; rp[i] = v; rmax = fmaxf(rmax, fabsf(v)); }
; #pragma unroll
;     for (int o_ = 1; o_ < 64; o_ <<= 1) rmax = fmaxf(rmax, __shfl_xor(rmax, o_));
;     return rmax;
; }
; DI void mixerD2_unit(int u, const bf16* PROJ, bf16* YC, float rmax, const float* kmax_l, LAS char* vt, int wave, int lane) {
;     const int b = u >> 6, h = (u >> 4) & 3, wu = (u & 15) * 8 + wave, rr = wu >> 2, cb = wu & 3, r = lane & 15, g = lane >> 4;
;     const bf16* kb = slab(PROJ, C_DK + h * 64, b); const bf16* vb = slab(PROJ, C_DV + h * 64, b);
;     const int qcol = 16 * cb + r, tq = 64 * rr + qcol;
;     const int cs = min(max(qcol - 8, 0), 48), rs = min(max(rr - 4, 0), 24), c0 = min(max(16 * cb - 8, 0), 32);
;     LAS float* rp = (LAS float*)(vt + 12288);
;     bf16x8 qf[2];
; #pragma unroll
;     for (int ks = 0; ks < 2; ++ks) qf[ks] = *(const bf16x8*)(slab(PROJ, C_DQ + h * 64, b) + (size_t)tq * 64 + 32 * ks + 8 * g);
;     const float bound = sqrtf(q_norm2(qf) * (kmax_l[b * 128 + 104 + 2 * h] + kmax_l[b * 128 + 105 + 2 * h])) * 1.01f + 0.05f + rmax;
;     const f32x4 cinit = {-bound, -bound, -bound, -bound};
;     f32x4 o[4], ol = {0.f, 0.f, 0.f, 0.f};
; #pragma unroll
;     for (int c = 0; c < 4; ++c) o[c] = ol;
;     const int tb0 = 64 * rs + c0, dr0 = rs - rr + 7;
;     const int kc0 = c0 + 4 * g - cs;
;     const LAS float* rpl = rp + dr0 * 31 + (c0 + 4 * g - qcol + 15);
;     TileRegs R0, R1, R2;
	v_mfma_f32_16x16x32_bf16 v[44:47], v[44:47], v[4:7], v[12:15]
	v_cndmask_b32_e64 v60, v234, v36, s[36:37]
	v_add_f32_e32 v36, v37, v61
	v_cndmask_b32_e64 v61, v234, v36, s[38:39]
	s_waitcnt lgkmcnt(3)
	v_add_f32_e32 v36, v38, v62
	v_cndmask_b32_e64 v62, v234, v36, s[40:41]
	v_add_f32_e32 v36, v39, v63
	v_cndmask_b32_e64 v63, v234, v36, s[42:43]
	s_waitcnt lgkmcnt(0)
	v_mfma_f32_16x16x32_bf16 v[36:39], v[52:55], v[8:11], v[44:47]
	s_nop 2
	v_exp_f32_e32 v44, v60
	v_exp_f32_e32 v47, v63
	s_nop 2
	v_add_f32_e32 v36, v36, v120
	v_add_f32_e32 v37, v37, v121
	v_cndmask_b32_e64 v36, v234, v36, s[44:45]
	v_cndmask_b32_e64 v37, v234, v37, s[46:47]
	v_add_f32_e32 v38, v38, v122
	v_add_f32_e32 v39, v39, v123
	v_exp_f32_e32 v45, v36
	v_exp_f32_e32 v36, v61
	v_exp_f32_e32 v46, v37
	v_exp_f32_e32 v37, v62
	v_cndmask_b32_e64 v38, v234, v38, s[48:49]
	v_cndmask_b32_e64 v39, v234, v39, s[50:51]
	v_exp_f32_e32 v52, v38
	v_exp_f32_e32 v39, v39
	v_cvt_pk_bf16_f32 v36, v44, v36
	v_cvt_pk_bf16_f32 v37, v37, v47
	v_cvt_pk_bf16_f32 v38, v45, v46
	ds_read_b64_tr_b16 v[46:47], v97 offset:2304
	ds_read_b64_tr_b16 v[44:45], v97
	v_cvt_pk_bf16_f32 v39, v52, v39
	s_nop 1
	v_mfma_f32_16x16x32_bf16 v[60:63], v[16:19], v[36:39], v[100:103]
	ds_read_b64_tr_b16 v[54:55], v97 offset:2336
	ds_read_b64_tr_b16 v[52:53], v97 offset:32
	s_nop 0
	ds_read_b64_tr_b16 v[100:101], v97 offset:64
	ds_read_b64_tr_b16 v[120:121], v97 offset:96
	ds_read_b64_tr_b16 v[102:103], v97 offset:2368
	ds_read_b64_tr_b16 v[122:123], v97 offset:2400
	s_waitcnt lgkmcnt(6)
	v_mfma_f32_16x16x32_bf16 v[108:111], v[44:47], v[36:39], v[108:111]
	v_lshl_add_u64 v[44:45], v[74:75], 0, v[188:189]
	v_lshl_add_u64 v[46:47], v[76:77], 0, v[188:189]
	v_add_lshl_u32 v188, s0, v85, 7
	global_load_dwordx4 v[124:127], v[44:45], off
	global_load_dwordx4 v[144:147], v[46:47], off
	v_lshl_add_u64 v[44:45], v[74:75], 0, v[188:189]
	s_waitcnt lgkmcnt(1)
	v_mfma_f32_16x16x32_bf16 v[100:103], v[100:103], v[36:39], v[116:119]
	v_lshl_add_u64 v[46:47], v[76:77], 0, v[188:189]
	s_nop 1
	global_load_dwordx4 v[116:119], v[44:45], off
	global_load_dwordx4 v[148:151], v[46:47], off
	s_waitcnt vmcnt(14)
	ds_write_b128 v95, v[48:51]
	ds_write_b128 v95, v[40:43] offset:4608
	s_waitcnt vmcnt(12)
	ds_write_b128 v95, v[64:67] offset:1152
	ds_write_b128 v95, v[56:59] offset:5760
	s_waitcnt vmcnt(10)
	ds_write_b128 v95, v[132:135] offset:2304
	ds_write_b128 v95, v[128:131] offset:6912
	s_waitcnt vmcnt(8)
	ds_write_b128 v95, v[140:143] offset:3456
	ds_write_b128 v95, v[136:139] offset:8064
	ds_read_b128 v[40:43], v96 offset:4608
	ds_read_b128 v[64:67], v96 offset:4672
	s_add_i32 s0, s55, 0x180
	v_or_b32_e32 v44, s0, v82
	s_waitcnt lgkmcnt(1)
	v_mfma_f32_16x16x32_bf16 v[40:43], v[40:43], v[4:7], v[12:15]
	v_lshlrev_b32_e32 v188, 7, v44
	v_lshl_add_u64 v[44:45], v[74:75], 0, v[188:189]
	v_lshl_add_u64 v[48:49], v[76:77], 0, v[188:189]
	v_add_lshl_u32 v188, s0, v83, 7
	v_mfma_f32_16x16x32_bf16 v[112:115], v[52:55], v[36:39], v[112:115]
	v_lshl_add_u64 v[52:53], v[74:75], 0, v[188:189]
	v_lshl_add_u64 v[56:57], v[76:77], 0, v[188:189]
	global_load_dwordx4 v[44:47], v[44:45], off
	s_nop 0
	global_load_dwordx4 v[48:51], v[48:49], off
	v_mfma_f32_16x16x32_bf16 v[36:39], v[120:123], v[36:39], v[104:107]
	global_load_dwordx4 v[52:55], v[52:53], off
	s_nop 0
	global_load_dwordx4 v[56:59], v[56:57], off
	ds_read2_b32 v[120:121], v73 offset1:1
	v_add_u32_e32 v104, 0x35d0, v71
	s_waitcnt lgkmcnt(1)
	v_mfma_f32_16x16x32_bf16 v[40:43], v[64:67], v[8:11], v[40:43]
	ds_read_b128 v[64:67], v96 offset:6912
	v_add_u32_e32 v73, 0x3598, v71
	v_add_u32_e32 v105, 0x35d8, v71
	ds_read2_b32 v[122:123], v73 offset1:1
	ds_read2_b32 v[128:129], v104 offset1:1
	ds_read2_b32 v[130:131], v105 offset1:1
	ds_read_b128 v[104:107], v96 offset:6976
	s_waitcnt lgkmcnt(5)
	v_add_f32_e32 v40, v40, v120
	s_waitcnt lgkmcnt(4)
	v_mfma_f32_16x16x32_bf16 v[64:67], v[64:67], v[4:7], v[12:15]
	v_cndmask_b32_e64 v73, v234, v40, s[36:37]
	v_add_f32_e32 v40, v41, v121
	v_cndmask_b32_e64 v120, v234, v40, s[38:39]
	s_waitcnt lgkmcnt(3)
	v_add_f32_e32 v40, v42, v122
	v_cndmask_b32_e64 v121, v234, v40, s[40:41]
	v_add_f32_e32 v40, v43, v123
	v_cndmask_b32_e64 v122, v234, v40, s[42:43]
	s_waitcnt lgkmcnt(0)
	v_mfma_f32_16x16x32_bf16 v[40:43], v[104:107], v[8:11], v[64:67]
	v_add_lshl_u32 v188, s0, v84, 7
	s_addk_i32 s55, 0x1c0
	v_lshl_add_u64 v[132:133], v[76:77], 0, v[188:189]
	v_exp_f32_e32 v64, v73
	v_exp_f32_e32 v67, v122
	s_nop 2
	v_add_f32_e32 v40, v40, v128
	v_add_f32_e32 v41, v41, v129
	v_cndmask_b32_e64 v40, v234, v40, s[44:45]
	v_cndmask_b32_e64 v41, v234, v41, s[46:47]
	v_exp_f32_e32 v65, v40
	v_exp_f32_e32 v40, v120
	v_exp_f32_e32 v66, v41
	v_exp_f32_e32 v41, v121
	v_add_f32_e32 v42, v42, v130
	v_add_f32_e32 v43, v43, v131
	v_cndmask_b32_e64 v42, v234, v42, s[48:49]
	v_cndmask_b32_e64 v43, v234, v43, s[50:51]
	v_exp_f32_e32 v73, v42
	v_exp_f32_e32 v43, v43
	v_cvt_pk_bf16_f32 v40, v64, v40
	v_cvt_pk_bf16_f32 v41, v41, v67
	v_cvt_pk_bf16_f32 v42, v65, v66
	ds_read_b64_tr_b16 v[66:67], v97 offset:2304
	ds_read_b64_tr_b16 v[64:65], v97
	ds_read_b64_tr_b16 v[106:107], v97 offset:2336
	ds_read_b64_tr_b16 v[104:105], v97 offset:32
	ds_read_b64_tr_b16 v[120:121], v97 offset:64
	ds_read_b64_tr_b16 v[128:129], v97 offset:96
	ds_read_b64_tr_b16 v[122:123], v97 offset:2368
	ds_read_b64_tr_b16 v[130:131], v97 offset:2400
	v_cvt_pk_bf16_f32 v43, v73, v43
	v_add_u32_e32 v73, s55, v83
	v_min_u32_e32 v73, 0x7ff, v73
	s_waitcnt lgkmcnt(6)
	v_mfma_f32_16x16x32_bf16 v[64:67], v[64:67], v[40:43], v[108:111]
	s_nop 2
	v_lshl_add_u64 v[108:109], v[74:75], 0, v[188:189]
	v_add_lshl_u32 v188, s0, v85, 7
	s_waitcnt lgkmcnt(0)
; DI void d_compute(f32x4 (&o)[4], f32x4& ol, const TileRegs& R, const bf16x8 (&qf)[2], const f32x4 cinit, int kr, int kc0, const LAS float* rpl, LAS char* vt, int lane) {
;     tile_v_to_lds(R, vt, lane);
;     const LAS float* rr_ = rpl + kr * 31;
;     f32x4 st[2];
; #pragma unroll
;     for (int t = 0; t < 2; ++t) {
;         st[t] = MFMA16(k_frag(vt, t, 0, lane), qf[0], cinit); st[t] = MFMA16(k_frag(vt, t, 1, lane), qf[1], st[t]);
; #pragma unroll
;         for (int i = 0; i < 4; ++i) { const bool ok = (unsigned)(kc0 + 16 * t + i) <= 15u;
;             const float v = st[t][i] + rr_[16 * t + i];
;             st[t][i] = ok ? v : -1e30f; }
;     }
;     fb_update(o, ol, st[0], st[1], vt, lane);
;     asm volatile("" ::: "memory");
; }
; DI float d_stage_rpb(const float* rpb_l, int h, LAS char* vt, int lane) {
;     LAS float* rp = (LAS float*)(vt + 12288); float rmax = 0.f;
;     for (int i = lane; i < 15 * 31; i += 64) { const float v = rpb_l[h * 465 + i] * LOG2E; rp[i] = v; rmax = fmaxf(rmax, fabsf(v)); }
; #pragma unroll
;     for (int o_ = 1; o_ < 64; o_ <<= 1) rmax = fmaxf(rmax, __shfl_xor(rmax, o_));
;     return rmax;
; }
; DI void mixerD2_unit(int u, const bf16* PROJ, bf16* YC, float rmax, const float* kmax_l, LAS char* vt, int wave, int lane) {
;     const int b = u >> 6, h = (u >> 4) & 3, wu = (u & 15) * 8 + wave, rr = wu >> 2, cb = wu & 3, r = lane & 15, g = lane >> 4;
;     const bf16* kb = slab(PROJ, C_DK + h * 64, b); const bf16* vb = slab(PROJ, C_DV + h * 64, b);
;     const int qcol = 16 * cb + r, tq = 64 * rr + qcol;
;     const int cs = min(max(qcol - 8, 0), 48), rs = min(max(rr - 4, 0), 24), c0 = min(max(16 * cb - 8, 0), 32);
;     LAS float* rp = (LAS float*)(vt + 12288);
;     bf16x8 qf[2];
; #pragma unroll
;     for (int ks = 0; ks < 2; ++ks) qf[ks] = *(const bf16x8*)(slab(PROJ, C_DQ + h * 64, b) + (size_t)tq * 64 + 32 * ks + 8 * g);
;     const float bound = sqrtf(q_norm2(qf) * (kmax_l[b * 128 + 104 + 2 * h] + kmax_l[b * 128 + 105 + 2 * h])) * 1.01f + 0.05f + rmax;
;     const f32x4 cinit = {-bound, -bound, -bound, -bound};
;     f32x4 o[4], ol = {0.f, 0.f, 0.f, 0.f};
; #pragma unroll
;     for (int c = 0; c < 4; ++c) o[c] = ol;
;     const int tb0 = 64 * rs + c0, dr0 = rs - rr + 7;
;     const int kc0 = c0 + 4 * g - cs;
;     const LAS float* rpl = rp + dr0 * 31 + (c0 + 4 * g - qcol + 15);
;     TileRegs R0, R1, R2;
	v_mfma_f32_16x16x32_bf16 v[128:131], v[128:131], v[40:43], v[36:39]
	v_lshl_add_u64 v[134:135], v[76:77], 0, v[188:189]
	s_mov_b64 s[0:1], 0x7800000
	s_nop 0
	v_or_b32_e32 v36, s55, v82
	v_mfma_f32_16x16x32_bf16 v[104:107], v[104:107], v[40:43], v[112:115]
	global_load_dwordx4 v[108:111], v[108:109], off
	s_nop 1
	global_load_dwordx4 v[112:115], v[132:133], off
	v_lshl_add_u64 v[132:133], v[74:75], 0, v[188:189]
	v_lshlrev_b32_e32 v188, 7, v36
	v_mfma_f32_16x16x32_bf16 v[60:63], v[16:19], v[40:43], v[60:63]
	v_lshl_add_u64 v[36:37], v[74:75], 0, v[188:189]
	v_mfma_f32_16x16x32_bf16 v[100:103], v[120:123], v[40:43], v[100:103]
	global_load_dwordx4 v[120:123], v[132:133], off
	s_nop 0
	global_load_dwordx4 v[132:135], v[134:135], off
	v_lshl_add_u64 v[40:41], v[76:77], 0, v[188:189]
	global_load_dwordx4 v[36:39], v[36:37], off
	s_nop 0
	global_load_dwordx4 v[40:43], v[40:41], off
	s_waitcnt vmcnt(16)
	ds_write_b128 v95, v[24:27]
	ds_write_b128 v95, v[20:23] offset:4608
	s_waitcnt vmcnt(14)
	ds_write_b128 v95, v[32:35] offset:1152
	ds_write_b128 v95, v[28:31] offset:5760
	s_waitcnt vmcnt(12)
	ds_write_b128 v95, v[144:147] offset:2304
	ds_write_b128 v95, v[124:127] offset:6912
	s_waitcnt vmcnt(10)
	ds_write_b128 v95, v[148:151] offset:3456
	ds_write_b128 v95, v[116:119] offset:8064
	ds_read_b128 v[24:27], v96 offset:4608
	v_lshlrev_b32_e32 v188, 7, v73
	v_lshl_add_u64 v[136:137], v[74:75], 0, v[188:189]
	v_add_u32_e32 v32, s55, v84
	v_lshl_add_u64 v[138:139], v[76:77], 0, v[188:189]
	global_load_dwordx4 v[20:23], v[136:137], off
	global_load_dwordx4 v[28:31], v[138:139], off
	v_min_u32_e32 v73, 0x7ff, v32
	ds_read_b128 v[32:35], v96 offset:4672
	s_waitcnt lgkmcnt(1)
	v_mfma_f32_16x16x32_bf16 v[24:27], v[24:27], v[4:7], v[12:15]
	v_lshlrev_b32_e32 v188, 7, v73
	v_lshl_add_u64 v[116:117], v[74:75], 0, v[188:189]
	v_lshl_add_u64 v[124:125], v[76:77], 0, v[188:189]
	v_add_u32_e32 v136, 0x360c, v71
	global_load_dwordx4 v[116:119], v[116:117], off
	s_nop 0
	global_load_dwordx4 v[124:127], v[124:125], off
	s_waitcnt lgkmcnt(0)
	v_mfma_f32_16x16x32_bf16 v[24:27], v[32:35], v[8:11], v[24:27]
	ds_read2_b32 v[140:141], v136 offset1:1
	ds_read_b128 v[32:35], v96 offset:6912
	v_add_u32_e32 v136, 0x3614, v71
	v_add_u32_e32 v137, 0x364c, v71
	v_add_u32_e32 v138, 0x3654, v71
	ds_read2_b32 v[142:143], v136 offset1:1
	ds_read2_b32 v[144:145], v137 offset1:1
	ds_read2_b32 v[146:147], v138 offset1:1
	ds_read_b128 v[136:139], v96 offset:6976
	s_waitcnt lgkmcnt(5)
	v_add_f32_e32 v24, v24, v140
	s_waitcnt lgkmcnt(4)
	v_mfma_f32_16x16x32_bf16 v[32:35], v[32:35], v[4:7], v[12:15]
	v_cndmask_b32_e64 v140, v234, v24, s[36:37]
	v_add_f32_e32 v24, v25, v141
	v_cndmask_b32_e64 v141, v234, v24, s[38:39]
	s_waitcnt lgkmcnt(3)
	v_add_f32_e32 v24, v26, v142
	v_cndmask_b32_e64 v142, v234, v24, s[40:41]
	v_add_f32_e32 v24, v27, v143
	v_cndmask_b32_e64 v143, v234, v24, s[42:43]
	s_waitcnt lgkmcnt(0)
	v_mfma_f32_16x16x32_bf16 v[24:27], v[136:139], v[8:11], v[32:35]
	v_add_u32_e32 v73, s55, v85
	s_nop 1
	v_exp_f32_e32 v32, v140
	v_exp_f32_e32 v35, v143
	s_nop 2
	v_add_f32_e32 v24, v24, v144
	v_add_f32_e32 v25, v25, v145
	v_cndmask_b32_e64 v24, v234, v24, s[44:45]
	v_cndmask_b32_e64 v25, v234, v25, s[46:47]
	v_exp_f32_e32 v33, v24
	v_exp_f32_e32 v24, v141
	v_exp_f32_e32 v34, v25
	v_exp_f32_e32 v25, v142
	v_add_f32_e32 v26, v26, v146
	v_add_f32_e32 v27, v27, v147
	v_cndmask_b32_e64 v26, v234, v26, s[48:49]
	v_cndmask_b32_e64 v27, v234, v27, s[50:51]
	v_exp_f32_e32 v136, v26
	v_exp_f32_e32 v27, v27
	v_cvt_pk_bf16_f32 v24, v32, v24
	v_cvt_pk_bf16_f32 v25, v25, v35
	v_cvt_pk_bf16_f32 v26, v33, v34
	ds_read_b64_tr_b16 v[34:35], v97 offset:2304
	ds_read_b64_tr_b16 v[32:33], v97
	v_cvt_pk_bf16_f32 v27, v136, v27
	ds_read_b64_tr_b16 v[138:139], v97 offset:2336
	ds_read_b64_tr_b16 v[136:137], v97 offset:32
	ds_read_b64_tr_b16 v[140:141], v97 offset:64
	ds_read_b64_tr_b16 v[144:145], v97 offset:96
	ds_read_b64_tr_b16 v[142:143], v97 offset:2368
	ds_read_b64_tr_b16 v[146:147], v97 offset:2400
	s_waitcnt lgkmcnt(6)
	v_mfma_f32_16x16x32_bf16 v[32:35], v[32:35], v[24:27], v[64:67]
	s_nop 2
	v_min_u32_e32 v64, 0x7ff, v73
	v_lshlrev_b32_e32 v188, 7, v64
	v_lshl_add_u64 v[74:75], v[74:75], 0, v[188:189]
	s_waitcnt lgkmcnt(4)
	v_mfma_f32_16x16x32_bf16 v[64:67], v[136:139], v[24:27], v[104:107]
	v_mov_b32_e32 v73, v189
	s_nop 1
	v_lshl_add_u64 v[104:105], v[76:77], 0, v[188:189]
	global_load_dwordx4 v[74:77], v[74:75], off
	s_nop 0
	global_load_dwordx4 v[104:107], v[104:105], off
	s_waitcnt vmcnt(14)
	ds_write_b128 v95, v[48:51]
	ds_write_b128 v95, v[44:47] offset:4608
	s_waitcnt vmcnt(12)
	ds_write_b128 v95, v[56:59] offset:1152
	ds_write_b128 v95, v[52:55] offset:5760
	s_waitcnt vmcnt(10)
	ds_write_b128 v95, v[112:115] offset:2304
	ds_write_b128 v95, v[108:111] offset:6912
	s_waitcnt vmcnt(8)
	ds_write_b128 v95, v[132:135] offset:3456
	ds_write_b128 v95, v[120:123] offset:8064
	ds_read_b128 v[44:47], v96 offset:4608
	ds_read_b128 v[48:51], v96 offset:4672
	v_add_u32_e32 v52, 0x3688, v71
	ds_read2_b32 v[56:57], v52 offset1:1
	s_waitcnt lgkmcnt(2)
	v_mfma_f32_16x16x32_bf16 v[44:47], v[44:47], v[4:7], v[12:15]
	v_add_u32_e32 v52, 0x3690, v71
	v_add_u32_e32 v53, 0x36c8, v71
	v_add_u32_e32 v54, 0x36d0, v71
	s_waitcnt lgkmcnt(1)
	v_mfma_f32_16x16x32_bf16 v[44:47], v[48:51], v[8:11], v[44:47]
	ds_read_b128 v[48:51], v96 offset:6912
	ds_read2_b32 v[58:59], v52 offset1:1
	ds_read2_b32 v[108:109], v53 offset1:1
	ds_read2_b32 v[110:111], v54 offset1:1
	ds_read_b128 v[52:55], v96 offset:6976
	s_waitcnt lgkmcnt(5)
	s_nop 1
	v_add_f32_e32 v44, v44, v56
	s_waitcnt lgkmcnt(4)
; DI void d_compute(f32x4 (&o)[4], f32x4& ol, const TileRegs& R, const bf16x8 (&qf)[2], const f32x4 cinit, int kr, int kc0, const LAS float* rpl, LAS char* vt, int lane) {
;     tile_v_to_lds(R, vt, lane);
;     const LAS float* rr_ = rpl + kr * 31;
;     f32x4 st[2];
; #pragma unroll
;     for (int t = 0; t < 2; ++t) {
;         st[t] = MFMA16(k_frag(vt, t, 0, lane), qf[0], cinit); st[t] = MFMA16(k_frag(vt, t, 1, lane), qf[1], st[t]);
; #pragma unroll
;         for (int i = 0; i < 4; ++i) { const bool ok = (unsigned)(kc0 + 16 * t + i) <= 15u;
;             const float v = st[t][i] + rr_[16 * t + i];
;             st[t][i] = ok ? v : -1e30f; }
;     }
;     fb_update(o, ol, st[0], st[1], vt, lane);
;     asm volatile("" ::: "memory");
; }
; DI float d_stage_rpb(const float* rpb_l, int h, LAS char* vt, int lane) {
;     LAS float* rp = (LAS float*)(vt + 12288); float rmax = 0.f;
;     for (int i = lane; i < 15 * 31; i += 64) { const float v = rpb_l[h * 465 + i] * LOG2E; rp[i] = v; rmax = fmaxf(rmax, fabsf(v)); }
; #pragma unroll
;     for (int o_ = 1; o_ < 64; o_ <<= 1) rmax = fmaxf(rmax, __shfl_xor(rmax, o_));
;     return rmax;
; }
; DI void mixerD2_unit(int u, const bf16* PROJ, bf16* YC, float rmax, const float* kmax_l, LAS char* vt, int wave, int lane) {
;     const int b = u >> 6, h = (u >> 4) & 3, wu = (u & 15) * 8 + wave, rr = wu >> 2, cb = wu & 3, r = lane & 15, g = lane >> 4;
;     const bf16* kb = slab(PROJ, C_DK + h * 64, b); const bf16* vb = slab(PROJ, C_DV + h * 64, b);
;     const int qcol = 16 * cb + r, tq = 64 * rr + qcol;
;     const int cs = min(max(qcol - 8, 0), 48), rs = min(max(rr - 4, 0), 24), c0 = min(max(16 * cb - 8, 0), 32);
;     LAS float* rp = (LAS float*)(vt + 12288);
;     bf16x8 qf[2];
; #pragma unroll
;     for (int ks = 0; ks < 2; ++ks) qf[ks] = *(const bf16x8*)(slab(PROJ, C_DQ + h * 64, b) + (size_t)tq * 64 + 32 * ks + 8 * g);
;     const float bound = sqrtf(q_norm2(qf) * (kmax_l[b * 128 + 104 + 2 * h] + kmax_l[b * 128 + 105 + 2 * h])) * 1.01f + 0.05f + rmax;
;     const f32x4 cinit = {-bound, -bound, -bound, -bound};
;     f32x4 o[4], ol = {0.f, 0.f, 0.f, 0.f};
; #pragma unroll
;     for (int c = 0; c < 4; ++c) o[c] = ol;
;     const int tb0 = 64 * rs + c0, dr0 = rs - rr + 7;
;     const int kc0 = c0 + 4 * g - cs;
;     const LAS float* rpl = rp + dr0 * 31 + (c0 + 4 * g - qcol + 15);
;     TileRegs R0, R1, R2;
	v_mfma_f32_16x16x32_bf16 v[48:51], v[48:51], v[4:7], v[12:15]
	v_cndmask_b32_e64 v56, v234, v44, s[36:37]
	v_add_f32_e32 v44, v45, v57
	v_cndmask_b32_e64 v57, v234, v44, s[38:39]
	s_waitcnt lgkmcnt(3)
	v_add_f32_e32 v44, v46, v58
	v_cndmask_b32_e64 v58, v234, v44, s[40:41]
	v_add_f32_e32 v44, v47, v59
	v_cndmask_b32_e64 v59, v234, v44, s[42:43]
	s_waitcnt lgkmcnt(0)
	v_mfma_f32_16x16x32_bf16 v[44:47], v[52:55], v[8:11], v[48:51]
	s_nop 2
	v_exp_f32_e32 v48, v56
	v_exp_f32_e32 v51, v59
	s_nop 2
	v_add_f32_e32 v44, v44, v108
	v_add_f32_e32 v45, v45, v109
	v_add_f32_e32 v46, v46, v110
	v_add_f32_e32 v47, v47, v111
	v_cndmask_b32_e64 v44, v234, v44, s[44:45]
	v_cndmask_b32_e64 v45, v234, v45, s[46:47]
	v_cndmask_b32_e64 v46, v234, v46, s[48:49]
	v_cndmask_b32_e64 v47, v234, v47, s[50:51]
	v_exp_f32_e32 v49, v44
	v_exp_f32_e32 v44, v57
	v_exp_f32_e32 v50, v45
	v_exp_f32_e32 v45, v58
	v_exp_f32_e32 v52, v46
	v_exp_f32_e32 v47, v47
	v_mfma_f32_16x16x32_bf16 v[60:63], v[16:19], v[24:27], v[60:63]
	v_cvt_pk_bf16_f32 v44, v48, v44
	v_cvt_pk_bf16_f32 v45, v45, v51
	v_cvt_pk_bf16_f32 v46, v49, v50
	v_cvt_pk_bf16_f32 v47, v52, v47
	ds_read_b64_tr_b16 v[50:51], v97 offset:2304
	ds_read_b64_tr_b16 v[48:49], v97
	v_mfma_f32_16x16x32_bf16 v[52:55], v[16:19], v[44:47], v[60:63]
	ds_read_b64_tr_b16 v[58:59], v97 offset:2336
	ds_read_b64_tr_b16 v[56:57], v97 offset:32
	s_nop 0
	ds_read_b64_tr_b16 v[60:61], v97 offset:64
	ds_read_b64_tr_b16 v[108:109], v97 offset:96
	ds_read_b64_tr_b16 v[62:63], v97 offset:2368
	ds_read_b64_tr_b16 v[110:111], v97 offset:2400
	s_waitcnt vmcnt(6)
	ds_write_b128 v95, v[40:43]
	ds_write_b128 v95, v[36:39] offset:4608
	s_waitcnt vmcnt(4)
	ds_write_b128 v95, v[28:31] offset:1152
	ds_write_b128 v95, v[20:23] offset:5760
	s_waitcnt vmcnt(2)
	ds_write_b128 v95, v[124:127] offset:2304
	ds_write_b128 v95, v[116:119] offset:6912
	s_waitcnt vmcnt(0)
	ds_write_b128 v95, v[104:107] offset:3456
	ds_write_b128 v95, v[74:77] offset:8064
	ds_read_b128 v[20:23], v96 offset:4608
	ds_read_b128 v[28:31], v96 offset:4672
	v_add_u32_e32 v36, 0x3704, v71
	ds_read2_b32 v[40:41], v36 offset1:1
	s_waitcnt lgkmcnt(2)
	v_mfma_f32_16x16x32_bf16 v[20:23], v[20:23], v[4:7], v[12:15]
	v_add_u32_e32 v36, 0x370c, v71
	v_add_u32_e32 v37, 0x3744, v71
	v_add_u32_e32 v38, 0x374c, v71
	v_mfma_f32_16x16x32_bf16 v[100:103], v[140:143], v[24:27], v[100:103]
	v_mfma_f32_16x16x32_bf16 v[24:27], v[144:147], v[24:27], v[128:131]
	s_waitcnt lgkmcnt(1)
	v_mfma_f32_16x16x32_bf16 v[20:23], v[28:31], v[8:11], v[20:23]
	ds_read_b128 v[28:31], v96 offset:6912
	v_mfma_f32_16x16x32_bf16 v[32:35], v[48:51], v[44:47], v[32:35]
	v_mfma_f32_16x16x32_bf16 v[48:51], v[56:59], v[44:47], v[64:67]
	s_waitcnt lgkmcnt(1)
	s_nop 3
	v_add_f32_e32 v20, v20, v40
	v_add_f32_e32 v21, v21, v41
	v_cndmask_b32_e64 v20, v234, v20, s[36:37]
	v_mfma_f32_16x16x32_bf16 v[56:59], v[60:63], v[44:47], v[100:103]
	v_cndmask_b32_e64 v21, v234, v21, s[38:39]
	v_or_b32_e32 v40, s54, v83
	v_ashrrev_i32_e32 v41, 31, v40
	v_mfma_f32_16x16x32_bf16 v[24:27], v[108:111], v[44:47], v[24:27]
	ds_read2_b32 v[42:43], v36 offset1:1
	ds_read2_b32 v[44:45], v37 offset1:1
	ds_read2_b32 v[46:47], v38 offset1:1
	ds_read_b128 v[36:39], v96 offset:6976
	s_waitcnt lgkmcnt(3)
	v_add_f32_e32 v22, v22, v42
	v_mfma_f32_16x16x32_bf16 v[4:7], v[28:31], v[4:7], v[12:15]
	v_add_u32_e32 v42, v88, v86
	s_nop 1
	v_add_f32_e32 v13, v23, v43
	s_waitcnt lgkmcnt(0)
	v_mfma_f32_16x16x32_bf16 v[4:7], v[36:39], v[8:11], v[4:7]
	v_cndmask_b32_e64 v12, v234, v22, s[40:41]
	v_cndmask_b32_e64 v13, v234, v13, s[42:43]
	v_exp_f32_e32 v10, v12
	v_exp_f32_e32 v11, v13
	s_nop 3
	v_add_f32_e32 v4, v4, v44
	v_add_f32_e32 v5, v5, v45
	v_add_f32_e32 v6, v6, v46
	v_add_f32_e32 v7, v7, v47
	v_cndmask_b32_e64 v4, v234, v4, s[44:45]
	v_cndmask_b32_e64 v5, v234, v5, s[46:47]
	v_cndmask_b32_e64 v6, v234, v6, s[48:49]
	v_cndmask_b32_e64 v7, v234, v7, s[50:51]
	v_exp_f32_e32 v8, v20
	v_exp_f32_e32 v4, v4
	v_exp_f32_e32 v9, v21
	v_exp_f32_e32 v5, v5
	v_exp_f32_e32 v14, v6
	v_exp_f32_e32 v15, v7
	v_cvt_pk_bf16_f32 v7, v10, v11
	ds_read_b64_tr_b16 v[12:13], v97 offset:2304
	ds_read_b64_tr_b16 v[10:11], v97
	v_cvt_pk_bf16_f32 v6, v8, v9
	v_cvt_pk_bf16_f32 v8, v4, v5
	v_cvt_pk_bf16_f32 v9, v14, v15
	v_lshl_add_u64 v[4:5], s[30:31], 0, v[72:73]
	v_lshlrev_b64 v[36:37], 7, v[40:41]
	s_waitcnt lgkmcnt(0)
	v_mfma_f32_16x16x32_bf16 v[10:13], v[10:13], v[6:9], v[32:35]
	s_nop 2
	v_lshl_add_u64 v[32:33], v[4:5], 0, s[0:1]
	v_or_b32_e32 v4, s54, v82
	v_ashrrev_i32_e32 v5, 31, v4
	v_mfma_f32_16x16x32_bf16 v[14:17], v[16:19], v[6:9], v[52:55]
	v_lshlrev_b64 v[34:35], 7, v[4:5]
	ds_read_b64_tr_b16 v[18:19], v97 offset:2336
	s_nop 5
	ds_read_b64_tr_b16 v[16:17], v97 offset:32
	ds_read_b64_tr_b16 v[20:21], v97 offset:64
	ds_read_b64_tr_b16 v[28:29], v97 offset:96
	ds_read_b64_tr_b16 v[22:23], v97 offset:2368
	ds_read_b64_tr_b16 v[30:31], v97 offset:2400
	v_lshl_add_u64 v[34:35], v[32:33], 0, v[34:35]
	v_lshl_add_u64 v[36:37], v[32:33], 0, v[36:37]
	global_load_dwordx4 v[32:35], v[34:35], off
	s_nop 0
	global_load_dwordx4 v[36:39], v[36:37], off
	s_waitcnt vmcnt(1)
	ds_write_b128 v42, v[32:35] offset:9216
	s_waitcnt vmcnt(0)
	ds_write_b128 v98, v[36:39] offset:9216
	v_div_scale_f32 v32, s[0:1], v14, v14, 1.0
	v_rcp_f32_e32 v33, v32
	v_add_u32_e32 v15, v87, v68
	v_add_u32_e32 v38, 0x2000, v15
	s_waitcnt lgkmcnt(6)
; #define LAS __attribute__((address_space(3)))
; DI unsigned pk2(float lo, float hi) { f32x2_t v = {lo, hi}; bf16x2_t b = __builtin_convertvector(v, bf16x2_t); return __builtin_bit_cast(unsigned, b); }
; DI float silu_f(float x) { return x * __builtin_amdgcn_rcpf(1.f + __expf(-x)); }
; DI void mixerD2_unit(int u, const bf16* PROJ, bf16* YC, float rmax, const float* kmax_l, LAS char* vt, int wave, int lane) {
;     ...
;     const float inv = 1.f / ol[0];
;     LAS char* sc = vt + SC_OFF; const int tok0 = 64 * rr + 16 * cb;
;     u32x2 gv[4];
;     rows16_load(sc, slab(PROJ, C_DG + h * 64, b), 64, tok0, 1, lane);
; #pragma unroll
;     for (int c = 0; c < 4; ++c) gv[c] = *(const LAS u32x2*)(sc + r * VT_PITCH + (16 * c + 4 * g) * 2);
; #pragma unroll
;     for (int c = 0; c < 4; ++c) { const f32x4 ov = o[c] * inv;
;         u32x2 w; w.x = pk2(ov[0] * silu_f(bflo(gv[c].x)), ov[1] * silu_f(bfhi(gv[c].x))); w.y = pk2(ov[2] * silu_f(bflo(gv[c].y)), ov[3] * silu_f(bfhi(gv[c].y)));
;         *(LAS u32x2*)(sc + r * VT_PITCH + (16 * c + 4 * g) * 2) = w; }
;     rows16_store(sc, YC + (size_t)b * T * 1024 + 768 + h * 64, 1024, tok0, 1, lane);
; }
; __global__ void __launch_bounds__(512) fwd_kernel(Args a) {
;     ...
;                 for (int u = blockIdx.x; u < 512; u += G) { const int hd = (u >> 4) & 3; if (hd != hcur) { rmax = d_stage_rpb(a.in[14] + l * 4 * 15 * 31, hd, vt, lane); hcur = hd; }
;                     mixerD2_unit(u, PROJ, YC, rmax, KMAX + l * 1024, vt, wave, lane); } }
	v_mfma_f32_16x16x32_bf16 v[16:19], v[16:19], v[6:9], v[48:51]
	v_fma_f32 v15, -v32, v33, 1.0
	v_fmac_f32_e32 v33, v15, v33
	v_div_scale_f32 v15, vcc, 1.0, v14, 1.0
	v_mul_f32_e32 v34, v15, v33
	s_waitcnt lgkmcnt(3)
	v_mfma_f32_16x16x32_bf16 v[20:23], v[20:23], v[6:9], v[56:59]
	v_fma_f32 v35, -v32, v34, v15
	v_fmac_f32_e32 v34, v35, v33
	v_fma_f32 v15, -v32, v34, v15
	s_waitcnt lgkmcnt(2)
	v_mfma_f32_16x16x32_bf16 v[6:9], v[28:31], v[6:9], v[24:27]
	s_nop 2
	ds_read2_b64 v[24:27], v38 offset0:128 offset1:132
	ds_read2_b64 v[28:31], v38 offset0:136 offset1:140
	v_div_fmas_f32 v15, v15, v33, v34
	v_div_fixup_f32 v14, v15, v14, 1.0
	v_pk_mul_f32 v[12:13], v[12:13], v[14:15] op_sel_hi:[1,0]
	s_waitcnt lgkmcnt(1)
	v_lshlrev_b32_e32 v32, 16, v24
	v_and_b32_e32 v33, 0xffff0000, v24
	v_mul_f32_e32 v15, 0xbfb8aa3b, v32
	v_exp_f32_e32 v15, v15
	v_mul_f32_e32 v24, 0xbfb8aa3b, v33
	v_exp_f32_e32 v34, v24
	v_and_b32_e32 v35, 0xffff0000, v25
	v_pk_mul_f32 v[10:11], v[10:11], v[14:15] op_sel_hi:[1,0]
	v_add_f32_e32 v15, 1.0, v15
	v_rcp_f32_e32 v24, v15
	v_add_f32_e32 v15, 1.0, v34
	v_lshlrev_b32_e32 v34, 16, v25
	v_mul_f32_e32 v25, 0xbfb8aa3b, v34
	v_exp_f32_e32 v36, v25
	v_mul_f32_e32 v25, 0xbfb8aa3b, v35
	v_exp_f32_e32 v37, v25
	v_rcp_f32_e32 v25, v15
	v_add_f32_e32 v15, 1.0, v36
	v_rcp_f32_e32 v36, v15
	v_add_f32_e32 v15, 1.0, v37
	v_rcp_f32_e32 v37, v15
	v_pk_mul_f32 v[24:25], v[24:25], v[32:33]
	s_lshl_b64 s[0:1], s[26:27], 22
	v_pk_mul_f32 v[10:11], v[10:11], v[24:25]
	v_pk_mul_f32 v[24:25], v[36:37], v[34:35]
	v_cvt_pk_bf16_f32 v10, v10, v11
	v_pk_mul_f32 v[12:13], v[12:13], v[24:25]
	s_add_u32 s0, s8, s0
	v_cvt_pk_bf16_f32 v11, v12, v13
	v_pk_mul_f32 v[12:13], v[14:15], v[18:19] op_sel_hi:[0,1]
	v_lshlrev_b32_e32 v18, 16, v26
	v_and_b32_e32 v19, 0xffff0000, v26
	v_mul_f32_e32 v15, 0xbfb8aa3b, v18
	v_exp_f32_e32 v15, v15
	v_mul_f32_e32 v24, 0xbfb8aa3b, v19
	v_exp_f32_e32 v25, v24
	v_lshlrev_b32_e32 v26, 16, v27
	v_pk_mul_f32 v[16:17], v[14:15], v[16:17] op_sel_hi:[0,1]
	v_add_f32_e32 v15, 1.0, v15
	v_rcp_f32_e32 v24, v15
	v_add_f32_e32 v15, 1.0, v25
	v_and_b32_e32 v27, 0xffff0000, v27
	v_mul_f32_e32 v25, 0xbfb8aa3b, v26
	v_exp_f32_e32 v32, v25
	v_mul_f32_e32 v25, 0xbfb8aa3b, v27
	v_exp_f32_e32 v33, v25
	v_rcp_f32_e32 v25, v15
	v_add_f32_e32 v15, 1.0, v32
	v_rcp_f32_e32 v32, v15
	v_add_f32_e32 v15, 1.0, v33
	v_rcp_f32_e32 v33, v15
	v_pk_mul_f32 v[18:19], v[24:25], v[18:19]
	s_addc_u32 s1, s9, s1
	v_pk_mul_f32 v[16:17], v[16:17], v[18:19]
	v_pk_mul_f32 v[18:19], v[32:33], v[26:27]
	v_cvt_pk_bf16_f32 v16, v16, v17
	v_pk_mul_f32 v[12:13], v[12:13], v[18:19]
	s_lshl_b32 s26, s53, 7
	v_cvt_pk_bf16_f32 v17, v12, v13
	s_waitcnt lgkmcnt(0)
	v_lshlrev_b32_e32 v12, 16, v28
	ds_write2_b64 v38, v[10:11], v[16:17] offset0:128 offset1:132
	v_pk_mul_f32 v[10:11], v[14:15], v[22:23] op_sel_hi:[0,1]
	v_and_b32_e32 v13, 0xffff0000, v28
	v_mul_f32_e32 v15, 0xbfb8aa3b, v12
	v_exp_f32_e32 v15, v15
	v_mul_f32_e32 v16, 0xbfb8aa3b, v13
	v_exp_f32_e32 v19, v16
	s_add_u32 s0, s0, s26
	v_pk_mul_f32 v[16:17], v[14:15], v[20:21] op_sel_hi:[0,1]
	v_add_f32_e32 v15, 1.0, v15
	v_lshlrev_b32_e32 v20, 16, v29
	v_rcp_f32_e32 v18, v15
	v_add_f32_e32 v15, 1.0, v19
	v_and_b32_e32 v21, 0xffff0000, v29
	v_mul_f32_e32 v19, 0xbfb8aa3b, v20
	v_exp_f32_e32 v22, v19
	v_mul_f32_e32 v19, 0xbfb8aa3b, v21
	v_exp_f32_e32 v23, v19
	v_rcp_f32_e32 v19, v15
	v_add_f32_e32 v15, 1.0, v22
	v_rcp_f32_e32 v22, v15
	v_add_f32_e32 v15, 1.0, v23
	v_rcp_f32_e32 v23, v15
	v_pk_mul_f32 v[12:13], v[18:19], v[12:13]
	v_pk_mul_f32 v[8:9], v[14:15], v[8:9] op_sel_hi:[0,1]
	v_pk_mul_f32 v[12:13], v[16:17], v[12:13]
	v_pk_mul_f32 v[16:17], v[22:23], v[20:21]
	v_cvt_pk_bf16_f32 v12, v12, v13
	v_pk_mul_f32 v[10:11], v[10:11], v[16:17]
	v_and_b32_e32 v17, 0xffff0000, v31
	v_cvt_pk_bf16_f32 v13, v10, v11
	v_lshlrev_b32_e32 v10, 16, v30
	v_and_b32_e32 v11, 0xffff0000, v30
	v_mul_f32_e32 v15, 0xbfb8aa3b, v10
	v_mul_f32_e32 v16, 0xbfb8aa3b, v11
	v_exp_f32_e32 v15, v15
	v_exp_f32_e32 v16, v16
	v_mul_f32_e32 v19, 0xbfb8aa3b, v17
	v_exp_f32_e32 v19, v19
	v_pk_mul_f32 v[6:7], v[14:15], v[6:7] op_sel_hi:[0,1]
	v_add_f32_e32 v14, 1.0, v15
	v_add_f32_e32 v15, 1.0, v16
	v_lshlrev_b32_e32 v16, 16, v31
	v_mul_f32_e32 v18, 0xbfb8aa3b, v16
	v_exp_f32_e32 v18, v18
	v_rcp_f32_e32 v14, v14
	v_rcp_f32_e32 v15, v15
	v_add_f32_e32 v19, 1.0, v19
	v_add_f32_e32 v18, 1.0, v18
	v_rcp_f32_e32 v18, v18
	v_rcp_f32_e32 v19, v19
	v_pk_mul_f32 v[10:11], v[14:15], v[10:11]
	s_addc_u32 s1, s1, 0
	v_pk_mul_f32 v[6:7], v[6:7], v[10:11]
	v_pk_mul_f32 v[10:11], v[18:19], v[16:17]
	v_cvt_pk_bf16_f32 v6, v6, v7
	v_pk_mul_f32 v[8:9], v[8:9], v[10:11]
	v_lshl_add_u64 v[14:15], s[0:1], 0, v[72:73]
	v_cvt_pk_bf16_f32 v7, v8, v9
	ds_write2_b64 v38, v[12:13], v[6:7] offset0:136 offset1:140
	ds_read_b128 v[6:9], v42 offset:9216
	ds_read_b128 v[10:13], v98 offset:9216
	v_lshlrev_b64 v[4:5], 11, v[4:5]
	v_lshl_add_u64 v[4:5], v[14:15], 0, v[4:5]
	s_add_i32 s52, s52, 2
	s_waitcnt lgkmcnt(1)
	global_store_dwordx4 v[4:5], v[6:9], off offset:1536
	v_lshlrev_b64 v[4:5], 11, v[40:41]
	v_lshl_add_u64 v[4:5], v[14:15], 0, v[4:5]
	s_bitcmp1_b32 s52, 1
	s_waitcnt lgkmcnt(0)
	global_store_dwordx4 v[4:5], v[10:13], off offset:1536
	s_cbranch_scc0 .LBB0_368
